# K loops: 4 of the 6 LDS-DMA loads of each 6-load segment issued inside the following MFMA block (vmcnt 8->4), all four GEMM instances
# speedup vs baseline: 1.0006x; 1.0006x over previous
; #define PG8_STAGE(bufoff, gbase, voff) do { _Pragma("unroll") for (int _i = 0; _i < 2; ++_i) \
;         __builtin_amdgcn_global_load_lds((const unsigned*)((const char*)(gbase) + (voff)[_i]), (PG8_LAS unsigned*)(lds + (bufoff) + ldsw + _i * 8192), 16, 0, 0); } while (0)
; #define PG8_LDA(dst, b, h) do { _Pragma("unroll") for (int m = 0; m < 4; ++m) _Pragma("unroll") for (int k = 0; k < 2; ++k) dst[m][k] = *(const PG8_LAS bf16x8*)(lds + PG8_SA(b, h) + aoff + m * 2048 + k * 1024); } while (0)
; #define PG8_LDB(dst, b, h) do { _Pragma("unroll") for (int n = 0; n < 2; ++n) _Pragma("unroll") for (int k = 0; k < 2; ++k) dst[n][k] = *(const PG8_LAS bf16x8*)(lds + PG8_SB(b, h) + boff + n * 2048 + k * 1024); } while (0)
; #define PG8_MMA(ai, bj, At, Bt) do { __builtin_amdgcn_s_setprio(1); _Pragma("unroll") for (int m = 0; m < 4; ++m) _Pragma("unroll") for (int n = 0; n < 2; ++n) _Pragma("unroll") for (int k = 0; k < 2; ++k) \
;         acc[ai][bj][m][n] = __builtin_amdgcn_mfma_f32_16x16x32_bf16(Bt[n][k], At[m][k], acc[ai][bj][m][n], 0, 0, 0); __builtin_amdgcn_s_setprio(0); } while (0)
; #define PG8_WAIT_V(n) asm volatile("s_waitcnt vmcnt(" #n ")" ::: "memory")
; #define PG8_WAIT_L(n) asm volatile("s_waitcnt lgkmcnt(" #n ")" ::: "memory")
; #define PG8_BAR __builtin_amdgcn_s_barrier()
; #define PG8_SCHED __builtin_amdgcn_sched_barrier(0)
; template <class Epi, class Sched, bool ALIGN_EPI = false, bool SP2 = false>
; __device__ __forceinline__ void gemm_phase(PG8_LAS unsigned char* lds, const Gemm g, const Sched& S, const Epi& E) {
;     ...
;         for (int t = 0; t < nt; t += 2) {
;             const bool last = (t == nt - 2);
;             const char* a1 = cA + (size_t)(t + 1) * kstep;
;             const char* a2 = last ? nA : cA + (size_t)(t + 2) * kstep; const char* b2 = last ? nB : cB + (size_t)(t + 2) * kstep;
;             const char* a3 = a2 + kstep; const char* b3 = b2 + kstep;
;             if (last && has_next) S.a_ready(nxt);
;             if constexpr (SP2) {
;             PG8_LDB(B0, 0, 0); PG8_LDB(B1, 0, 1); PG8_SCHED; PG8_LDA(At, 0, 0); PG8_STAGE(PG8_SA(1, 1), a1 + hstep, voffA);
;             PG8_WAIT_V(8); PG8_WAIT_L(0); PG8_BAR; PG8_MMA(0, 0, At, B0); PG8_MMA(0, 1, At, B1); PG8_BAR; PG8_SCHED;
;             PG8_LDA(At, 0, 1); PG8_STAGE(PG8_SB(0, 0), b2, voffB); PG8_STAGE(PG8_SB(0, 1), b2 + hstep, voffB); PG8_STAGE(PG8_SA(0, 0), a2, voffA);
.LBB0_165:
	s_add_u32 s68, s42, 0xfff80080
	s_addc_u32 s69, s43, -1
	s_add_i32 s82, 0, 0x10000
	s_cmp_eq_u32 s71, 28
	s_cselect_b32 s81, s47, s69
	s_cselect_b32 s80, s55, s68
	v_add_u32_e32 v144, s82, v147
	s_cselect_b32 s79, s45, s63
	s_cselect_b32 s78, s58, s59
	s_add_i32 s83, 0, 0x14000
	ds_read_b128 v[140:143], v144
	ds_read_b128 v[156:159], v144 offset:1024
	ds_read_b128 v[160:163], v144 offset:2048
	ds_read_b128 v[164:167], v144 offset:3072
	v_add_u32_e32 v144, s83, v147
	ds_read_b128 v[168:171], v144
	ds_read_b128 v[172:175], v144 offset:1024
	ds_read_b128 v[192:195], v144 offset:2048
	ds_read_b128 v[196:199], v144 offset:3072
	v_lshl_add_u64 v[150:151], s[42:43], 0, v[136:137]
	s_add_i32 m0, s14, 0xc000
	ds_read_b128 v[200:203], v149
	ds_read_b128 v[204:207], v149 offset:1024
	ds_read_b128 v[208:211], v149 offset:2048
	ds_read_b128 v[212:215], v149 offset:3072
	ds_read_b128 v[216:219], v149 offset:4096
	ds_read_b128 v[220:223], v149 offset:5120
	ds_read_b128 v[224:227], v149 offset:6144
	ds_read_b128 v[228:231], v149 offset:7168
	global_load_lds_dwordx4 v[150:151], off
	v_lshl_add_u64 v[150:151], s[42:43], 0, v[138:139]
	s_add_i32 m0, s14, 0xe000
	s_nop 0
	global_load_lds_dwordx4 v[150:151], off
	s_waitcnt vmcnt(8)
	s_waitcnt lgkmcnt(0)
	s_barrier
	s_setprio 1
	s_waitcnt lgkmcnt(0)
	v_mfma_f32_16x16x32_bf16 v[124:127], v[140:143], v[200:203], v[124:127]
	v_mfma_f32_16x16x32_bf16 v[120:123], v[160:163], v[200:203], v[120:123]
	v_mfma_f32_16x16x32_bf16 v[108:111], v[140:143], v[208:211], v[108:111]
	v_mfma_f32_16x16x32_bf16 v[104:107], v[160:163], v[208:211], v[104:107]
	v_mfma_f32_16x16x32_bf16 v[92:95], v[140:143], v[216:219], v[92:95]
	v_mfma_f32_16x16x32_bf16 v[88:91], v[160:163], v[216:219], v[88:91]
	v_mfma_f32_16x16x32_bf16 v[76:79], v[140:143], v[224:227], v[76:79]
	v_mfma_f32_16x16x32_bf16 v[72:75], v[160:163], v[224:227], v[72:75]
	v_mfma_f32_16x16x32_bf16 v[124:127], v[156:159], v[204:207], v[124:127]
	v_mfma_f32_16x16x32_bf16 v[120:123], v[164:167], v[204:207], v[120:123]
	v_mfma_f32_16x16x32_bf16 v[108:111], v[156:159], v[212:215], v[108:111]
	v_mfma_f32_16x16x32_bf16 v[104:107], v[164:167], v[212:215], v[104:107]
	v_mfma_f32_16x16x32_bf16 v[92:95], v[156:159], v[220:223], v[92:95]
	v_mfma_f32_16x16x32_bf16 v[88:91], v[164:167], v[220:223], v[88:91]
	v_mfma_f32_16x16x32_bf16 v[76:79], v[156:159], v[228:231], v[76:79]
	v_mfma_f32_16x16x32_bf16 v[72:75], v[164:167], v[228:231], v[72:75]
	s_setprio 0
	s_setprio 1
	v_mfma_f32_16x16x32_bf16 v[116:119], v[168:171], v[200:203], v[116:119]
	v_mfma_f32_16x16x32_bf16 v[112:115], v[192:195], v[200:203], v[112:115]
	v_mfma_f32_16x16x32_bf16 v[100:103], v[168:171], v[208:211], v[100:103]
	v_mfma_f32_16x16x32_bf16 v[96:99], v[192:195], v[208:211], v[96:99]
	v_mfma_f32_16x16x32_bf16 v[84:87], v[168:171], v[216:219], v[84:87]
	v_mfma_f32_16x16x32_bf16 v[80:83], v[192:195], v[216:219], v[80:83]
	v_mfma_f32_16x16x32_bf16 v[68:71], v[168:171], v[224:227], v[68:71]
	v_mfma_f32_16x16x32_bf16 v[64:67], v[192:195], v[224:227], v[64:67]
	v_mfma_f32_16x16x32_bf16 v[116:119], v[172:175], v[204:207], v[116:119]
	v_mfma_f32_16x16x32_bf16 v[112:115], v[196:199], v[204:207], v[112:115]
	v_mfma_f32_16x16x32_bf16 v[100:103], v[172:175], v[212:215], v[100:103]
	v_mfma_f32_16x16x32_bf16 v[96:99], v[196:199], v[212:215], v[96:99]
	v_mfma_f32_16x16x32_bf16 v[84:87], v[172:175], v[220:223], v[84:87]
	v_mfma_f32_16x16x32_bf16 v[80:83], v[196:199], v[220:223], v[80:83]
	v_mfma_f32_16x16x32_bf16 v[68:71], v[172:175], v[228:231], v[68:71]
	v_mfma_f32_16x16x32_bf16 v[64:67], v[196:199], v[228:231], v[64:67]
	s_setprio 0
	s_barrier
	s_add_i32 s68, s82, s0
	v_lshl_add_u64 v[150:151], s[78:79], 0, v[152:153]
	s_mov_b32 m0, s68
	ds_read_b128 v[200:203], v149 offset:16384
	ds_read_b128 v[204:207], v149 offset:17408
	ds_read_b128 v[208:211], v149 offset:18432
	ds_read_b128 v[212:215], v149 offset:19456
	ds_read_b128 v[216:219], v149 offset:20480
	ds_read_b128 v[220:223], v149 offset:21504
	ds_read_b128 v[224:227], v149 offset:22528
	ds_read_b128 v[228:231], v149 offset:23552
	global_load_lds_dwordx4 v[150:151], off
	s_add_i32 m0, s68, 0x2000
	s_add_u32 s68, s78, 0x80000
	v_lshl_add_u64 v[182:183], s[78:79], 0, v[128:129]
	s_addc_u32 s69, s79, 0
	s_add_i32 s82, s83, s0
	global_load_lds_dwordx4 v[182:183], off
	v_lshl_add_u64 v[184:185], s[68:69], 0, v[152:153]
	v_lshl_add_u64 v[232:233], s[68:69], 0, v[152:153]
	v_lshl_add_u64 v[188:189], s[80:81], 0, v[130:131]
	v_lshl_add_u64 v[184:185], s[68:69], 0, v[128:129]
	v_lshl_add_u64 v[234:235], s[68:69], 0, v[128:129]
	v_lshl_add_u64 v[184:185], s[80:81], 0, v[132:133]
	v_lshl_add_u64 v[240:241], s[80:81], 0, v[132:133]
	v_lshl_add_u64 v[242:243], v[188:189], 0, 0
	s_waitcnt vmcnt(4)
	s_waitcnt lgkmcnt(0)
	s_barrier
; #define PG8_STAGE(bufoff, gbase, voff) do { _Pragma("unroll") for (int _i = 0; _i < 2; ++_i) \
;         __builtin_amdgcn_global_load_lds((const unsigned*)((const char*)(gbase) + (voff)[_i]), (PG8_LAS unsigned*)(lds + (bufoff) + ldsw + _i * 8192), 16, 0, 0); } while (0)
; #define PG8_LDA(dst, b, h) do { _Pragma("unroll") for (int m = 0; m < 4; ++m) _Pragma("unroll") for (int k = 0; k < 2; ++k) dst[m][k] = *(const PG8_LAS bf16x8*)(lds + PG8_SA(b, h) + aoff + m * 2048 + k * 1024); } while (0)
; #define PG8_LDB(dst, b, h) do { _Pragma("unroll") for (int n = 0; n < 2; ++n) _Pragma("unroll") for (int k = 0; k < 2; ++k) dst[n][k] = *(const PG8_LAS bf16x8*)(lds + PG8_SB(b, h) + boff + n * 2048 + k * 1024); } while (0)
; #define PG8_MMA(ai, bj, At, Bt) do { __builtin_amdgcn_s_setprio(1); _Pragma("unroll") for (int m = 0; m < 4; ++m) _Pragma("unroll") for (int n = 0; n < 2; ++n) _Pragma("unroll") for (int k = 0; k < 2; ++k) \
;         acc[ai][bj][m][n] = __builtin_amdgcn_mfma_f32_16x16x32_bf16(Bt[n][k], At[m][k], acc[ai][bj][m][n], 0, 0, 0); __builtin_amdgcn_s_setprio(0); } while (0)
; #define PG8_WAIT_V(n) asm volatile("s_waitcnt vmcnt(" #n ")" ::: "memory")
; #define PG8_WAIT_L(n) asm volatile("s_waitcnt lgkmcnt(" #n ")" ::: "memory")
; #define PG8_BAR __builtin_amdgcn_s_barrier()
; #define PG8_SCHED __builtin_amdgcn_sched_barrier(0)
; template <class Epi, class Sched, bool ALIGN_EPI = false, bool SP2 = false>
; __device__ __forceinline__ void gemm_phase(PG8_LAS unsigned char* lds, const Gemm g, const Sched& S, const Epi& E) {
;     ...
;             PG8_LDA(At, 0, 1); PG8_STAGE(PG8_SB(0, 0), b2, voffB); PG8_STAGE(PG8_SB(0, 1), b2 + hstep, voffB); PG8_STAGE(PG8_SA(0, 0), a2, voffA);
;             PG8_WAIT_V(8); PG8_WAIT_L(0); PG8_BAR; PG8_MMA(1, 0, At, B0); PG8_MMA(1, 1, At, B1); PG8_BAR; PG8_SCHED;
;             PG8_LDB(B0, 1, 0); PG8_LDB(B1, 1, 1); PG8_SCHED; PG8_LDA(At, 1, 0); PG8_STAGE(PG8_SA(0, 1), a2 + hstep, voffA);
;             PG8_WAIT_V(8); PG8_WAIT_L(0); PG8_BAR; PG8_MMA(0, 0, At, B0); PG8_MMA(0, 1, At, B1); PG8_BAR; PG8_SCHED;
	s_setprio 1
	s_waitcnt lgkmcnt(0)
	v_mfma_f32_16x16x32_bf16 v[60:63], v[140:143], v[200:203], v[60:63]
	s_mov_b32 m0, s82
	v_mfma_f32_16x16x32_bf16 v[56:59], v[160:163], v[200:203], v[56:59]
	global_load_lds_dwordx4 v[232:233], off
	v_mfma_f32_16x16x32_bf16 v[44:47], v[140:143], v[208:211], v[44:47]
	v_mfma_f32_16x16x32_bf16 v[40:43], v[160:163], v[208:211], v[40:43]
	v_mfma_f32_16x16x32_bf16 v[28:31], v[140:143], v[216:219], v[28:31]
	v_mfma_f32_16x16x32_bf16 v[24:27], v[160:163], v[216:219], v[24:27]
	v_mfma_f32_16x16x32_bf16 v[12:15], v[140:143], v[224:227], v[12:15]
	v_mfma_f32_16x16x32_bf16 v[8:11], v[160:163], v[224:227], v[8:11]
	v_mfma_f32_16x16x32_bf16 v[60:63], v[156:159], v[204:207], v[60:63]
	s_add_i32 m0, s82, 0x2000
	v_mfma_f32_16x16x32_bf16 v[56:59], v[164:167], v[204:207], v[56:59]
	global_load_lds_dwordx4 v[234:235], off
	v_mfma_f32_16x16x32_bf16 v[44:47], v[156:159], v[212:215], v[44:47]
	v_mfma_f32_16x16x32_bf16 v[40:43], v[164:167], v[212:215], v[40:43]
	v_mfma_f32_16x16x32_bf16 v[28:31], v[156:159], v[220:223], v[28:31]
	v_mfma_f32_16x16x32_bf16 v[24:27], v[164:167], v[220:223], v[24:27]
	v_mfma_f32_16x16x32_bf16 v[12:15], v[156:159], v[228:231], v[12:15]
	v_mfma_f32_16x16x32_bf16 v[8:11], v[164:167], v[228:231], v[8:11]
	s_setprio 0
	s_setprio 1
	v_mfma_f32_16x16x32_bf16 v[52:55], v[168:171], v[200:203], v[52:55]
	s_mov_b32 m0, s14
	v_mfma_f32_16x16x32_bf16 v[48:51], v[192:195], v[200:203], v[48:51]
	global_load_lds_dwordx4 v[240:241], off
	v_mfma_f32_16x16x32_bf16 v[36:39], v[168:171], v[208:211], v[36:39]
	v_mfma_f32_16x16x32_bf16 v[32:35], v[192:195], v[208:211], v[32:35]
	v_mfma_f32_16x16x32_bf16 v[20:23], v[168:171], v[216:219], v[20:23]
	v_mfma_f32_16x16x32_bf16 v[16:19], v[192:195], v[216:219], v[16:19]
	v_mfma_f32_16x16x32_bf16 v[4:7], v[168:171], v[224:227], v[4:7]
	v_mfma_f32_16x16x32_bf16 v[0:3], v[192:195], v[224:227], v[0:3]
	v_mfma_f32_16x16x32_bf16 v[52:55], v[172:175], v[204:207], v[52:55]
	s_mov_b32 m0, s15
	v_mfma_f32_16x16x32_bf16 v[48:51], v[196:199], v[204:207], v[48:51]
	global_load_lds_dwordx4 v[242:243], off
	v_mfma_f32_16x16x32_bf16 v[36:39], v[172:175], v[212:215], v[36:39]
	v_mfma_f32_16x16x32_bf16 v[32:35], v[196:199], v[212:215], v[32:35]
	v_mfma_f32_16x16x32_bf16 v[20:23], v[172:175], v[220:223], v[20:23]
	v_mfma_f32_16x16x32_bf16 v[16:19], v[196:199], v[220:223], v[16:19]
	v_mfma_f32_16x16x32_bf16 v[4:7], v[172:175], v[228:231], v[4:7]
	v_mfma_f32_16x16x32_bf16 v[0:3], v[196:199], v[228:231], v[0:3]
	s_setprio 0
	s_barrier
	v_add_u32_e32 v144, s93, v147
	s_add_i32 s82, 0, 0x1c000
	ds_read_b128 v[140:143], v144
	ds_read_b128 v[156:159], v144 offset:1024
	ds_read_b128 v[160:163], v144 offset:2048
	ds_read_b128 v[164:167], v144 offset:3072
	v_add_u32_e32 v144, s82, v147
	ds_read_b128 v[168:171], v144
	ds_read_b128 v[172:175], v144 offset:1024
	ds_read_b128 v[192:195], v144 offset:2048
	ds_read_b128 v[196:199], v144 offset:3072
	s_add_u32 s68, s80, 0x80000
	s_addc_u32 s69, s81, 0
	s_mov_b32 m0, s16
	v_lshl_add_u64 v[190:191], s[68:69], 0, v[132:133]
	ds_read_b128 v[200:203], v149 offset:32768
	ds_read_b128 v[204:207], v149 offset:33792
	ds_read_b128 v[208:211], v149 offset:34816
	ds_read_b128 v[212:215], v149 offset:35840
	ds_read_b128 v[216:219], v149 offset:36864
	ds_read_b128 v[220:223], v149 offset:37888
	ds_read_b128 v[224:227], v149 offset:38912
	ds_read_b128 v[228:231], v149 offset:39936
	global_load_lds_dwordx4 v[190:191], off
	v_lshl_add_u64 v[190:191], s[68:69], 0, v[130:131]
	s_mov_b32 m0, s17
	s_nop 0
	global_load_lds_dwordx4 v[190:191], off
	s_waitcnt vmcnt(8)
	s_waitcnt lgkmcnt(0)
	s_barrier
	s_setprio 1
	s_waitcnt lgkmcnt(0)
	v_mfma_f32_16x16x32_bf16 v[124:127], v[140:143], v[200:203], v[124:127]
	v_mfma_f32_16x16x32_bf16 v[120:123], v[160:163], v[200:203], v[120:123]
	v_mfma_f32_16x16x32_bf16 v[108:111], v[140:143], v[208:211], v[108:111]
	v_mfma_f32_16x16x32_bf16 v[104:107], v[160:163], v[208:211], v[104:107]
	v_mfma_f32_16x16x32_bf16 v[92:95], v[140:143], v[216:219], v[92:95]
	v_mfma_f32_16x16x32_bf16 v[88:91], v[160:163], v[216:219], v[88:91]
	v_mfma_f32_16x16x32_bf16 v[76:79], v[140:143], v[224:227], v[76:79]
	v_mfma_f32_16x16x32_bf16 v[72:75], v[160:163], v[224:227], v[72:75]
	v_mfma_f32_16x16x32_bf16 v[124:127], v[156:159], v[204:207], v[124:127]
	v_mfma_f32_16x16x32_bf16 v[120:123], v[164:167], v[204:207], v[120:123]
	v_mfma_f32_16x16x32_bf16 v[108:111], v[156:159], v[212:215], v[108:111]
	v_mfma_f32_16x16x32_bf16 v[104:107], v[164:167], v[212:215], v[104:107]
	v_mfma_f32_16x16x32_bf16 v[92:95], v[156:159], v[220:223], v[92:95]
	v_mfma_f32_16x16x32_bf16 v[88:91], v[164:167], v[220:223], v[88:91]
	v_mfma_f32_16x16x32_bf16 v[76:79], v[156:159], v[228:231], v[76:79]
	v_mfma_f32_16x16x32_bf16 v[72:75], v[164:167], v[228:231], v[72:75]
	s_setprio 0
	s_setprio 1
	v_mfma_f32_16x16x32_bf16 v[116:119], v[168:171], v[200:203], v[116:119]
	v_mfma_f32_16x16x32_bf16 v[112:115], v[192:195], v[200:203], v[112:115]
	v_mfma_f32_16x16x32_bf16 v[100:103], v[168:171], v[208:211], v[100:103]
	v_mfma_f32_16x16x32_bf16 v[96:99], v[192:195], v[208:211], v[96:99]
	v_mfma_f32_16x16x32_bf16 v[84:87], v[168:171], v[216:219], v[84:87]
	v_mfma_f32_16x16x32_bf16 v[80:83], v[192:195], v[216:219], v[80:83]
	v_mfma_f32_16x16x32_bf16 v[68:71], v[168:171], v[224:227], v[68:71]
	v_mfma_f32_16x16x32_bf16 v[64:67], v[192:195], v[224:227], v[64:67]
	v_mfma_f32_16x16x32_bf16 v[116:119], v[172:175], v[204:207], v[116:119]
	v_mfma_f32_16x16x32_bf16 v[112:115], v[196:199], v[204:207], v[112:115]
	v_mfma_f32_16x16x32_bf16 v[100:103], v[172:175], v[212:215], v[100:103]
	v_mfma_f32_16x16x32_bf16 v[96:99], v[196:199], v[212:215], v[96:99]
	v_mfma_f32_16x16x32_bf16 v[84:87], v[172:175], v[220:223], v[84:87]
	v_mfma_f32_16x16x32_bf16 v[80:83], v[196:199], v[220:223], v[80:83]
	v_mfma_f32_16x16x32_bf16 v[68:71], v[172:175], v[228:231], v[68:71]
	v_mfma_f32_16x16x32_bf16 v[64:67], v[196:199], v[228:231], v[64:67]
	s_setprio 0
	s_barrier
; #define PG8_STAGE(bufoff, gbase, voff) do { _Pragma("unroll") for (int _i = 0; _i < 2; ++_i) \
;         __builtin_amdgcn_global_load_lds((const unsigned*)((const char*)(gbase) + (voff)[_i]), (PG8_LAS unsigned*)(lds + (bufoff) + ldsw + _i * 8192), 16, 0, 0); } while (0)
; #define PG8_LDA(dst, b, h) do { _Pragma("unroll") for (int m = 0; m < 4; ++m) _Pragma("unroll") for (int k = 0; k < 2; ++k) dst[m][k] = *(const PG8_LAS bf16x8*)(lds + PG8_SA(b, h) + aoff + m * 2048 + k * 1024); } while (0)
; #define PG8_WAIT_V(n) asm volatile("s_waitcnt vmcnt(" #n ")" ::: "memory")
; template <class Epi, class Sched, bool ALIGN_EPI = false, bool SP2 = false>
; __device__ __forceinline__ void gemm_phase(PG8_LAS unsigned char* lds, const Gemm g, const Sched& S, const Epi& E) {
;     ...
;             PG8_LDA(At, 1, 1); PG8_STAGE(PG8_SB(1, 0), b3, voffB); PG8_STAGE(PG8_SB(1, 1), b3 + hstep, voffB); PG8_STAGE(PG8_SA(1, 0), a3, voffA);
;             PG8_WAIT_V(8); PG8_WAIT_L(0); PG8_BAR; PG8_MMA(1, 0, At, B0); PG8_MMA(1, 1, At, B1); PG8_BAR; PG8_SCHED;
;             } else {
;             PG8_LDB(B0, 0, 0); PG8_SCHED; PG8_LDA(At, 0, 0); PG8_STAGE(PG8_SA(1, 1), a1 + hstep, voffA);
;             PG8_WAIT_L(8); PG8_BAR; PG8_WAIT_L(0); PG8_MMA(0, 0, At, B0); PG8_BAR; PG8_SCHED;
;             PG8_LDB(B1, 0, 1); PG8_STAGE(PG8_SB(0, 0), b2, voffB);
;             PG8_BAR; PG8_WAIT_L(0); PG8_MMA(0, 1, At, B1); PG8_BAR;
;             PG8_LDA(At, 0, 1); PG8_STAGE(PG8_SA(0, 0), a2, voffA);
;             PG8_BAR; PG8_WAIT_L(0); PG8_MMA(1, 0, At, B0); PG8_BAR; PG8_SCHED;
;             PG8_STAGE(PG8_SB(0, 1), b2 + hstep, voffB);
;             PG8_WAIT_V(6); PG8_BAR; PG8_MMA(1, 1, At, B1); PG8_BAR;
;             PG8_LDB(B0, 1, 0); PG8_SCHED; PG8_LDA(At, 1, 0); PG8_STAGE(PG8_SA(0, 1), a2 + hstep, voffA);
;             PG8_WAIT_L(8); PG8_BAR; PG8_WAIT_L(0); PG8_MMA(0, 0, At, B0); PG8_BAR; PG8_SCHED;
;             PG8_LDB(B1, 1, 1); PG8_STAGE(PG8_SB(1, 0), b3, voffB);
;             PG8_BAR; PG8_WAIT_L(0); PG8_MMA(0, 1, At, B1); PG8_BAR;
;             PG8_LDA(At, 1, 1); PG8_STAGE(PG8_SA(1, 0), a3, voffA);
;             PG8_BAR; PG8_WAIT_L(0); PG8_MMA(1, 0, At, B0); PG8_BAR; PG8_SCHED;
;             PG8_STAGE(PG8_SB(1, 1), b3 + hstep, voffB);
;             PG8_WAIT_V(6); PG8_BAR; PG8_MMA(1, 1, At, B1); PG8_BAR;
;             }
;         }
;         if constexpr (ALIGN_EPI) { if (wr == 0) PG8_BAR; }
	s_add_i32 s68, s93, s0
	v_lshl_add_u64 v[150:151], v[150:151], 0, s[18:19]
	s_mov_b32 m0, s68
	ds_read_b128 v[200:203], v149 offset:49152
	ds_read_b128 v[204:207], v149 offset:50176
	ds_read_b128 v[208:211], v149 offset:51200
	ds_read_b128 v[212:215], v149 offset:52224
	ds_read_b128 v[216:219], v149 offset:53248
	ds_read_b128 v[220:223], v149 offset:54272
	ds_read_b128 v[224:227], v149 offset:55296
	ds_read_b128 v[228:231], v149 offset:56320
	global_load_lds_dwordx4 v[150:151], off
	s_add_i32 m0, s68, 0x2000
	s_add_u32 s68, s78, 0x80080
	v_lshl_add_u64 v[150:151], v[182:183], 0, s[18:19]
	s_addc_u32 s69, s79, 0
	s_add_i32 s78, s82, s0
	global_load_lds_dwordx4 v[150:151], off
	v_lshl_add_u64 v[150:151], s[68:69], 0, v[152:153]
	v_lshl_add_u64 v[232:233], s[68:69], 0, v[152:153]
	v_lshl_add_u64 v[150:151], s[68:69], 0, v[128:129]
	v_lshl_add_u64 v[234:235], s[68:69], 0, v[128:129]
	v_lshl_add_u64 v[150:151], v[184:185], 0, s[18:19]
	v_lshl_add_u64 v[240:241], v[184:185], 0, s[18:19]
	v_lshl_add_u64 v[150:151], v[188:189], 0, s[18:19]
	v_lshl_add_u64 v[242:243], v[188:189], 0, s[18:19]
	s_waitcnt vmcnt(4)
	s_waitcnt lgkmcnt(0)
	s_barrier
	s_setprio 1
	s_waitcnt lgkmcnt(0)
	v_mfma_f32_16x16x32_bf16 v[60:63], v[140:143], v[200:203], v[60:63]
	s_mov_b32 m0, s78
	v_mfma_f32_16x16x32_bf16 v[56:59], v[160:163], v[200:203], v[56:59]
	global_load_lds_dwordx4 v[232:233], off
	v_mfma_f32_16x16x32_bf16 v[44:47], v[140:143], v[208:211], v[44:47]
	v_mfma_f32_16x16x32_bf16 v[40:43], v[160:163], v[208:211], v[40:43]
	v_mfma_f32_16x16x32_bf16 v[28:31], v[140:143], v[216:219], v[28:31]
	v_mfma_f32_16x16x32_bf16 v[24:27], v[160:163], v[216:219], v[24:27]
	v_mfma_f32_16x16x32_bf16 v[12:15], v[140:143], v[224:227], v[12:15]
	v_mfma_f32_16x16x32_bf16 v[8:11], v[160:163], v[224:227], v[8:11]
	v_mfma_f32_16x16x32_bf16 v[60:63], v[156:159], v[204:207], v[60:63]
	s_add_i32 m0, s78, 0x2000
	v_mfma_f32_16x16x32_bf16 v[56:59], v[164:167], v[204:207], v[56:59]
	global_load_lds_dwordx4 v[234:235], off
	v_mfma_f32_16x16x32_bf16 v[44:47], v[156:159], v[212:215], v[44:47]
	v_mfma_f32_16x16x32_bf16 v[40:43], v[164:167], v[212:215], v[40:43]
	v_mfma_f32_16x16x32_bf16 v[28:31], v[156:159], v[220:223], v[28:31]
	v_mfma_f32_16x16x32_bf16 v[24:27], v[164:167], v[220:223], v[24:27]
	v_mfma_f32_16x16x32_bf16 v[12:15], v[156:159], v[228:231], v[12:15]
	v_mfma_f32_16x16x32_bf16 v[8:11], v[164:167], v[228:231], v[8:11]
	s_setprio 0
	s_setprio 1
	v_mfma_f32_16x16x32_bf16 v[52:55], v[168:171], v[200:203], v[52:55]
	s_mov_b32 m0, s22
	v_mfma_f32_16x16x32_bf16 v[48:51], v[192:195], v[200:203], v[48:51]
	global_load_lds_dwordx4 v[240:241], off
	v_mfma_f32_16x16x32_bf16 v[36:39], v[168:171], v[208:211], v[36:39]
	v_mfma_f32_16x16x32_bf16 v[32:35], v[192:195], v[208:211], v[32:35]
	v_mfma_f32_16x16x32_bf16 v[20:23], v[168:171], v[216:219], v[20:23]
	v_mfma_f32_16x16x32_bf16 v[16:19], v[192:195], v[216:219], v[16:19]
	v_mfma_f32_16x16x32_bf16 v[4:7], v[168:171], v[224:227], v[4:7]
	v_mfma_f32_16x16x32_bf16 v[0:3], v[192:195], v[224:227], v[0:3]
	v_mfma_f32_16x16x32_bf16 v[52:55], v[172:175], v[204:207], v[52:55]
	s_mov_b32 m0, s23
	v_mfma_f32_16x16x32_bf16 v[48:51], v[196:199], v[204:207], v[48:51]
	global_load_lds_dwordx4 v[242:243], off
	v_mfma_f32_16x16x32_bf16 v[36:39], v[172:175], v[212:215], v[36:39]
	v_mfma_f32_16x16x32_bf16 v[32:35], v[196:199], v[212:215], v[32:35]
	v_mfma_f32_16x16x32_bf16 v[20:23], v[172:175], v[220:223], v[20:23]
	v_mfma_f32_16x16x32_bf16 v[16:19], v[196:199], v[220:223], v[16:19]
	v_mfma_f32_16x16x32_bf16 v[4:7], v[172:175], v[228:231], v[4:7]
	v_mfma_f32_16x16x32_bf16 v[0:3], v[196:199], v[228:231], v[0:3]
	s_setprio 0
	s_barrier
	s_add_i32 s71, s71, 2
	s_add_u32 s42, s42, 0x100
	s_addc_u32 s43, s43, 0
	s_add_u32 s59, s59, 0x100
	s_addc_u32 s63, s63, 0
	s_cmp_gt_u32 s71, 29
	s_cbranch_scc0 .LBB0_165
	s_and_b64 vcc, exec, s[24:25]
	s_cbranch_vccz .LBB0_168
	s_barrier

; #define PG8_STAGE(bufoff, gbase, voff) do { _Pragma("unroll") for (int _i = 0; _i < 2; ++_i) \
;         __builtin_amdgcn_global_load_lds((const unsigned*)((const char*)(gbase) + (voff)[_i]), (PG8_LAS unsigned*)(lds + (bufoff) + ldsw + _i * 8192), 16, 0, 0); } while (0)
; #define PG8_LDA(dst, b, h) do { _Pragma("unroll") for (int m = 0; m < 4; ++m) _Pragma("unroll") for (int k = 0; k < 2; ++k) dst[m][k] = *(const PG8_LAS bf16x8*)(lds + PG8_SA(b, h) + aoff + m * 2048 + k * 1024); } while (0)
; #define PG8_LDB(dst, b, h) do { _Pragma("unroll") for (int n = 0; n < 2; ++n) _Pragma("unroll") for (int k = 0; k < 2; ++k) dst[n][k] = *(const PG8_LAS bf16x8*)(lds + PG8_SB(b, h) + boff + n * 2048 + k * 1024); } while (0)
; #define PG8_MMA(ai, bj, At, Bt) do { __builtin_amdgcn_s_setprio(1); _Pragma("unroll") for (int m = 0; m < 4; ++m) _Pragma("unroll") for (int n = 0; n < 2; ++n) _Pragma("unroll") for (int k = 0; k < 2; ++k) \
;         acc[ai][bj][m][n] = __builtin_amdgcn_mfma_f32_16x16x32_bf16(Bt[n][k], At[m][k], acc[ai][bj][m][n], 0, 0, 0); __builtin_amdgcn_s_setprio(0); } while (0)
; #define PG8_WAIT_V(n) asm volatile("s_waitcnt vmcnt(" #n ")" ::: "memory")
; #define PG8_WAIT_L(n) asm volatile("s_waitcnt lgkmcnt(" #n ")" ::: "memory")
; #define PG8_BAR __builtin_amdgcn_s_barrier()
; #define PG8_SCHED __builtin_amdgcn_sched_barrier(0)
; template <class Epi, class Sched, bool ALIGN_EPI = false, bool SP2 = false>
; __device__ __forceinline__ void gemm_phase(PG8_LAS unsigned char* lds, const Gemm g, const Sched& S, const Epi& E) {
;     ...
;         for (int t = 0; t < nt; t += 2) {
;             const bool last = (t == nt - 2);
;             const char* a1 = cA + (size_t)(t + 1) * kstep;
;             const char* a2 = last ? nA : cA + (size_t)(t + 2) * kstep; const char* b2 = last ? nB : cB + (size_t)(t + 2) * kstep;
;             const char* a3 = a2 + kstep; const char* b3 = b2 + kstep;
;             if (last && has_next) S.a_ready(nxt);
;             if constexpr (SP2) {
;             PG8_LDB(B0, 0, 0); PG8_LDB(B1, 0, 1); PG8_SCHED; PG8_LDA(At, 0, 0); PG8_STAGE(PG8_SA(1, 1), a1 + hstep, voffA);
;             PG8_WAIT_V(8); PG8_WAIT_L(0); PG8_BAR; PG8_MMA(0, 0, At, B0); PG8_MMA(0, 1, At, B1); PG8_BAR; PG8_SCHED;
;             PG8_LDA(At, 0, 1); PG8_STAGE(PG8_SB(0, 0), b2, voffB); PG8_STAGE(PG8_SB(0, 1), b2 + hstep, voffB); PG8_STAGE(PG8_SA(0, 0), a2, voffA);
.LBB0_218:
	s_add_i32 vcc_lo, s46, 2
	s_add_u32 s68, s44, 0x80
	s_addc_u32 s47, s45, 0
	s_add_i32 vcc_hi, 0, 0x10000
	s_cmp_eq_u32 s15, s46
	s_cselect_b32 s47, s83, s47
	s_cselect_b32 s46, s82, s68
	v_add_u32_e32 v146, vcc_hi, v149
	s_cselect_b32 s69, s85, s87
	s_cselect_b32 s68, s84, s86
	s_add_i32 s96, 0, 0x14000
	ds_read_b128 v[138:141], v146
	ds_read_b128 v[142:145], v146 offset:1024
	ds_read_b128 v[156:159], v146 offset:2048
	ds_read_b128 v[160:163], v146 offset:3072
	v_add_u32_e32 v146, s96, v149
	ds_read_b128 v[164:167], v146
	ds_read_b128 v[168:171], v146 offset:1024
	ds_read_b128 v[172:175], v146 offset:2048
	ds_read_b128 v[192:195], v146 offset:3072
	v_lshl_add_u64 v[146:147], s[44:45], 0, v[134:135]
	s_add_i32 m0, s54, 0xc000
	ds_read_b128 v[196:199], v151
	ds_read_b128 v[200:203], v151 offset:1024
	ds_read_b128 v[204:207], v151 offset:2048
	ds_read_b128 v[208:211], v151 offset:3072
	ds_read_b128 v[212:215], v151 offset:4096
	ds_read_b128 v[216:219], v151 offset:5120
	ds_read_b128 v[220:223], v151 offset:6144
	ds_read_b128 v[224:227], v151 offset:7168
	global_load_lds_dwordx4 v[146:147], off
	v_lshl_add_u64 v[146:147], s[44:45], 0, v[136:137]
	s_add_i32 m0, s54, 0xe000
	s_nop 0
	global_load_lds_dwordx4 v[146:147], off
	s_waitcnt vmcnt(8)
	s_waitcnt lgkmcnt(0)
	s_barrier
	s_setprio 1
	s_waitcnt lgkmcnt(0)
	v_mfma_f32_16x16x32_bf16 v[124:127], v[138:141], v[196:199], v[124:127]
	v_mfma_f32_16x16x32_bf16 v[120:123], v[156:159], v[196:199], v[120:123]
	v_mfma_f32_16x16x32_bf16 v[108:111], v[138:141], v[204:207], v[108:111]
	v_mfma_f32_16x16x32_bf16 v[104:107], v[156:159], v[204:207], v[104:107]
	v_mfma_f32_16x16x32_bf16 v[92:95], v[138:141], v[212:215], v[92:95]
	v_mfma_f32_16x16x32_bf16 v[88:91], v[156:159], v[212:215], v[88:91]
	v_mfma_f32_16x16x32_bf16 v[76:79], v[138:141], v[220:223], v[76:79]
	v_mfma_f32_16x16x32_bf16 v[72:75], v[156:159], v[220:223], v[72:75]
	v_mfma_f32_16x16x32_bf16 v[124:127], v[142:145], v[200:203], v[124:127]
	v_mfma_f32_16x16x32_bf16 v[120:123], v[160:163], v[200:203], v[120:123]
	v_mfma_f32_16x16x32_bf16 v[108:111], v[142:145], v[208:211], v[108:111]
	v_mfma_f32_16x16x32_bf16 v[104:107], v[160:163], v[208:211], v[104:107]
	v_mfma_f32_16x16x32_bf16 v[92:95], v[142:145], v[216:219], v[92:95]
	v_mfma_f32_16x16x32_bf16 v[88:91], v[160:163], v[216:219], v[88:91]
	v_mfma_f32_16x16x32_bf16 v[76:79], v[142:145], v[224:227], v[76:79]
	v_mfma_f32_16x16x32_bf16 v[72:75], v[160:163], v[224:227], v[72:75]
	s_setprio 0
	s_setprio 1
	v_mfma_f32_16x16x32_bf16 v[116:119], v[164:167], v[196:199], v[116:119]
	v_mfma_f32_16x16x32_bf16 v[112:115], v[172:175], v[196:199], v[112:115]
	v_mfma_f32_16x16x32_bf16 v[100:103], v[164:167], v[204:207], v[100:103]
	v_mfma_f32_16x16x32_bf16 v[96:99], v[172:175], v[204:207], v[96:99]
	v_mfma_f32_16x16x32_bf16 v[84:87], v[164:167], v[212:215], v[84:87]
	v_mfma_f32_16x16x32_bf16 v[80:83], v[172:175], v[212:215], v[80:83]
	v_mfma_f32_16x16x32_bf16 v[68:71], v[164:167], v[220:223], v[68:71]
	v_mfma_f32_16x16x32_bf16 v[64:67], v[172:175], v[220:223], v[64:67]
	v_mfma_f32_16x16x32_bf16 v[116:119], v[168:171], v[200:203], v[116:119]
	v_mfma_f32_16x16x32_bf16 v[112:115], v[192:195], v[200:203], v[112:115]
	v_mfma_f32_16x16x32_bf16 v[100:103], v[168:171], v[208:211], v[100:103]
	v_mfma_f32_16x16x32_bf16 v[96:99], v[192:195], v[208:211], v[96:99]
	v_mfma_f32_16x16x32_bf16 v[84:87], v[168:171], v[216:219], v[84:87]
	v_mfma_f32_16x16x32_bf16 v[80:83], v[192:195], v[216:219], v[80:83]
	v_mfma_f32_16x16x32_bf16 v[68:71], v[168:171], v[224:227], v[68:71]
	v_mfma_f32_16x16x32_bf16 v[64:67], v[192:195], v[224:227], v[64:67]
	s_setprio 0
	s_barrier
	s_add_i32 vcc_hi, vcc_hi, s63
	v_lshl_add_u64 v[146:147], s[68:69], 0, v[152:153]
	s_mov_b32 m0, vcc_hi
	ds_read_b128 v[196:199], v151 offset:16384
	ds_read_b128 v[200:203], v151 offset:17408
	ds_read_b128 v[204:207], v151 offset:18432
	ds_read_b128 v[208:211], v151 offset:19456
	ds_read_b128 v[212:215], v151 offset:20480
	ds_read_b128 v[216:219], v151 offset:21504
	ds_read_b128 v[220:223], v151 offset:22528
	ds_read_b128 v[224:227], v151 offset:23552
	global_load_lds_dwordx4 v[146:147], off
	s_add_i32 m0, vcc_hi, 0x2000
	v_lshl_add_u64 v[182:183], s[68:69], 0, v[128:129]
	s_add_u32 s68, s68, s48
	s_addc_u32 s69, s69, 0
	s_add_i32 s96, s96, s63
	global_load_lds_dwordx4 v[182:183], off
	v_lshl_add_u64 v[184:185], s[68:69], 0, v[152:153]
	v_lshl_add_u64 v[232:233], s[68:69], 0, v[152:153]
	v_lshl_add_u64 v[188:189], s[68:69], 0, v[128:129]
	v_lshl_add_u64 v[190:191], s[46:47], 0, v[132:133]
	v_lshl_add_u64 v[234:235], v[188:189], 0, 0
	v_lshl_add_u64 v[228:229], s[46:47], 0, v[130:131]
	v_lshl_add_u64 v[240:241], v[190:191], 0, 0
	v_lshl_add_u64 v[242:243], v[228:229], 0, 0
	s_waitcnt vmcnt(4)
	s_waitcnt lgkmcnt(0)
	s_barrier
; #define PG8_STAGE(bufoff, gbase, voff) do { _Pragma("unroll") for (int _i = 0; _i < 2; ++_i) \
;         __builtin_amdgcn_global_load_lds((const unsigned*)((const char*)(gbase) + (voff)[_i]), (PG8_LAS unsigned*)(lds + (bufoff) + ldsw + _i * 8192), 16, 0, 0); } while (0)
; #define PG8_LDA(dst, b, h) do { _Pragma("unroll") for (int m = 0; m < 4; ++m) _Pragma("unroll") for (int k = 0; k < 2; ++k) dst[m][k] = *(const PG8_LAS bf16x8*)(lds + PG8_SA(b, h) + aoff + m * 2048 + k * 1024); } while (0)
; #define PG8_LDB(dst, b, h) do { _Pragma("unroll") for (int n = 0; n < 2; ++n) _Pragma("unroll") for (int k = 0; k < 2; ++k) dst[n][k] = *(const PG8_LAS bf16x8*)(lds + PG8_SB(b, h) + boff + n * 2048 + k * 1024); } while (0)
; #define PG8_MMA(ai, bj, At, Bt) do { __builtin_amdgcn_s_setprio(1); _Pragma("unroll") for (int m = 0; m < 4; ++m) _Pragma("unroll") for (int n = 0; n < 2; ++n) _Pragma("unroll") for (int k = 0; k < 2; ++k) \
;         acc[ai][bj][m][n] = __builtin_amdgcn_mfma_f32_16x16x32_bf16(Bt[n][k], At[m][k], acc[ai][bj][m][n], 0, 0, 0); __builtin_amdgcn_s_setprio(0); } while (0)
; #define PG8_WAIT_V(n) asm volatile("s_waitcnt vmcnt(" #n ")" ::: "memory")
; #define PG8_WAIT_L(n) asm volatile("s_waitcnt lgkmcnt(" #n ")" ::: "memory")
; #define PG8_BAR __builtin_amdgcn_s_barrier()
; #define PG8_SCHED __builtin_amdgcn_sched_barrier(0)
; template <class Epi, class Sched, bool ALIGN_EPI = false, bool SP2 = false>
; __device__ __forceinline__ void gemm_phase(PG8_LAS unsigned char* lds, const Gemm g, const Sched& S, const Epi& E) {
;     ...
;             PG8_LDA(At, 0, 1); PG8_STAGE(PG8_SB(0, 0), b2, voffB); PG8_STAGE(PG8_SB(0, 1), b2 + hstep, voffB); PG8_STAGE(PG8_SA(0, 0), a2, voffA);
;             PG8_WAIT_V(8); PG8_WAIT_L(0); PG8_BAR; PG8_MMA(1, 0, At, B0); PG8_MMA(1, 1, At, B1); PG8_BAR; PG8_SCHED;
;             PG8_LDB(B0, 1, 0); PG8_LDB(B1, 1, 1); PG8_SCHED; PG8_LDA(At, 1, 0); PG8_STAGE(PG8_SA(0, 1), a2 + hstep, voffA);
;             PG8_WAIT_V(8); PG8_WAIT_L(0); PG8_BAR; PG8_MMA(0, 0, At, B0); PG8_MMA(0, 1, At, B1); PG8_BAR; PG8_SCHED;
	s_setprio 1
	s_waitcnt lgkmcnt(0)
	v_mfma_f32_16x16x32_bf16 v[60:63], v[138:141], v[196:199], v[60:63]
	s_mov_b32 m0, s96
	v_mfma_f32_16x16x32_bf16 v[56:59], v[156:159], v[196:199], v[56:59]
	global_load_lds_dwordx4 v[232:233], off
	v_mfma_f32_16x16x32_bf16 v[44:47], v[138:141], v[204:207], v[44:47]
	v_mfma_f32_16x16x32_bf16 v[40:43], v[156:159], v[204:207], v[40:43]
	v_mfma_f32_16x16x32_bf16 v[28:31], v[138:141], v[212:215], v[28:31]
	v_mfma_f32_16x16x32_bf16 v[24:27], v[156:159], v[212:215], v[24:27]
	v_mfma_f32_16x16x32_bf16 v[12:15], v[138:141], v[220:223], v[12:15]
	v_mfma_f32_16x16x32_bf16 v[8:11], v[156:159], v[220:223], v[8:11]
	v_mfma_f32_16x16x32_bf16 v[60:63], v[142:145], v[200:203], v[60:63]
	s_add_i32 m0, s96, 0x2000
	v_mfma_f32_16x16x32_bf16 v[56:59], v[160:163], v[200:203], v[56:59]
	global_load_lds_dwordx4 v[234:235], off
	v_mfma_f32_16x16x32_bf16 v[44:47], v[142:145], v[208:211], v[44:47]
	v_mfma_f32_16x16x32_bf16 v[40:43], v[160:163], v[208:211], v[40:43]
	v_mfma_f32_16x16x32_bf16 v[28:31], v[142:145], v[216:219], v[28:31]
	v_mfma_f32_16x16x32_bf16 v[24:27], v[160:163], v[216:219], v[24:27]
	v_mfma_f32_16x16x32_bf16 v[12:15], v[142:145], v[224:227], v[12:15]
	v_mfma_f32_16x16x32_bf16 v[8:11], v[160:163], v[224:227], v[8:11]
	s_setprio 0
	s_setprio 1
	v_mfma_f32_16x16x32_bf16 v[52:55], v[164:167], v[196:199], v[52:55]
	s_mov_b32 m0, s54
	v_mfma_f32_16x16x32_bf16 v[48:51], v[172:175], v[196:199], v[48:51]
	global_load_lds_dwordx4 v[240:241], off
	v_mfma_f32_16x16x32_bf16 v[36:39], v[164:167], v[204:207], v[36:39]
	v_mfma_f32_16x16x32_bf16 v[32:35], v[172:175], v[204:207], v[32:35]
	v_mfma_f32_16x16x32_bf16 v[20:23], v[164:167], v[212:215], v[20:23]
	v_mfma_f32_16x16x32_bf16 v[16:19], v[172:175], v[212:215], v[16:19]
	v_mfma_f32_16x16x32_bf16 v[4:7], v[164:167], v[220:223], v[4:7]
	v_mfma_f32_16x16x32_bf16 v[0:3], v[172:175], v[220:223], v[0:3]
	v_mfma_f32_16x16x32_bf16 v[52:55], v[168:171], v[200:203], v[52:55]
	s_mov_b32 m0, s55
	v_mfma_f32_16x16x32_bf16 v[48:51], v[192:195], v[200:203], v[48:51]
	global_load_lds_dwordx4 v[242:243], off
	v_mfma_f32_16x16x32_bf16 v[36:39], v[168:171], v[208:211], v[36:39]
	v_mfma_f32_16x16x32_bf16 v[32:35], v[192:195], v[208:211], v[32:35]
	v_mfma_f32_16x16x32_bf16 v[20:23], v[168:171], v[216:219], v[20:23]
	v_mfma_f32_16x16x32_bf16 v[16:19], v[192:195], v[216:219], v[16:19]
	v_mfma_f32_16x16x32_bf16 v[4:7], v[168:171], v[224:227], v[4:7]
	v_mfma_f32_16x16x32_bf16 v[0:3], v[192:195], v[224:227], v[0:3]
	s_setprio 0
	s_barrier
	v_add_u32_e32 v155, s93, v149
	s_add_i32 s68, 0, 0x1c000
	ds_read_b128 v[138:141], v155
	ds_read_b128 v[142:145], v155 offset:1024
	ds_read_b128 v[156:159], v155 offset:2048
	ds_read_b128 v[160:163], v155 offset:3072
	v_add_u32_e32 v155, s68, v149
	ds_read_b128 v[164:167], v155
	ds_read_b128 v[168:171], v155 offset:1024
	ds_read_b128 v[172:175], v155 offset:2048
	ds_read_b128 v[192:195], v155 offset:3072
	s_add_u32 s46, s46, s48
	s_addc_u32 s47, s47, 0
	s_mov_b32 m0, s34
	v_lshl_add_u64 v[230:231], s[46:47], 0, v[132:133]
	ds_read_b128 v[196:199], v151 offset:32768
	ds_read_b128 v[200:203], v151 offset:33792
	ds_read_b128 v[204:207], v151 offset:34816
	ds_read_b128 v[208:211], v151 offset:35840
	ds_read_b128 v[212:215], v151 offset:36864
	ds_read_b128 v[216:219], v151 offset:37888
	ds_read_b128 v[220:223], v151 offset:38912
	ds_read_b128 v[224:227], v151 offset:39936
	global_load_lds_dwordx4 v[230:231], off
	v_lshl_add_u64 v[230:231], s[46:47], 0, v[130:131]
	s_mov_b32 m0, s95
	s_nop 0
	global_load_lds_dwordx4 v[230:231], off
	s_waitcnt vmcnt(8)
	s_waitcnt lgkmcnt(0)
	s_barrier
	s_setprio 1
	s_waitcnt lgkmcnt(0)
	v_mfma_f32_16x16x32_bf16 v[124:127], v[138:141], v[196:199], v[124:127]
	v_mfma_f32_16x16x32_bf16 v[120:123], v[156:159], v[196:199], v[120:123]
	v_mfma_f32_16x16x32_bf16 v[108:111], v[138:141], v[204:207], v[108:111]
	v_mfma_f32_16x16x32_bf16 v[104:107], v[156:159], v[204:207], v[104:107]
	v_mfma_f32_16x16x32_bf16 v[92:95], v[138:141], v[212:215], v[92:95]
	v_mfma_f32_16x16x32_bf16 v[88:91], v[156:159], v[212:215], v[88:91]
	v_mfma_f32_16x16x32_bf16 v[76:79], v[138:141], v[220:223], v[76:79]
	v_mfma_f32_16x16x32_bf16 v[72:75], v[156:159], v[220:223], v[72:75]
	v_mfma_f32_16x16x32_bf16 v[124:127], v[142:145], v[200:203], v[124:127]
	v_mfma_f32_16x16x32_bf16 v[120:123], v[160:163], v[200:203], v[120:123]
	v_mfma_f32_16x16x32_bf16 v[108:111], v[142:145], v[208:211], v[108:111]
	v_mfma_f32_16x16x32_bf16 v[104:107], v[160:163], v[208:211], v[104:107]
	v_mfma_f32_16x16x32_bf16 v[92:95], v[142:145], v[216:219], v[92:95]
	v_mfma_f32_16x16x32_bf16 v[88:91], v[160:163], v[216:219], v[88:91]
	v_mfma_f32_16x16x32_bf16 v[76:79], v[142:145], v[224:227], v[76:79]
	v_mfma_f32_16x16x32_bf16 v[72:75], v[160:163], v[224:227], v[72:75]
	s_setprio 0
	s_setprio 1
	v_mfma_f32_16x16x32_bf16 v[116:119], v[164:167], v[196:199], v[116:119]
	v_mfma_f32_16x16x32_bf16 v[112:115], v[172:175], v[196:199], v[112:115]
	v_mfma_f32_16x16x32_bf16 v[100:103], v[164:167], v[204:207], v[100:103]
	v_mfma_f32_16x16x32_bf16 v[96:99], v[172:175], v[204:207], v[96:99]
	v_mfma_f32_16x16x32_bf16 v[84:87], v[164:167], v[212:215], v[84:87]
	v_mfma_f32_16x16x32_bf16 v[80:83], v[172:175], v[212:215], v[80:83]
	v_mfma_f32_16x16x32_bf16 v[68:71], v[164:167], v[220:223], v[68:71]
	v_mfma_f32_16x16x32_bf16 v[64:67], v[172:175], v[220:223], v[64:67]
	v_mfma_f32_16x16x32_bf16 v[116:119], v[168:171], v[200:203], v[116:119]
	v_mfma_f32_16x16x32_bf16 v[112:115], v[192:195], v[200:203], v[112:115]
	v_mfma_f32_16x16x32_bf16 v[100:103], v[168:171], v[208:211], v[100:103]
	v_mfma_f32_16x16x32_bf16 v[96:99], v[192:195], v[208:211], v[96:99]
	v_mfma_f32_16x16x32_bf16 v[84:87], v[168:171], v[216:219], v[84:87]
	v_mfma_f32_16x16x32_bf16 v[80:83], v[192:195], v[216:219], v[80:83]
	v_mfma_f32_16x16x32_bf16 v[68:71], v[168:171], v[224:227], v[68:71]
	v_mfma_f32_16x16x32_bf16 v[64:67], v[192:195], v[224:227], v[64:67]
	s_setprio 0
	s_barrier
; #define PG8_STAGE(bufoff, gbase, voff) do { _Pragma("unroll") for (int _i = 0; _i < 2; ++_i) \
;         __builtin_amdgcn_global_load_lds((const unsigned*)((const char*)(gbase) + (voff)[_i]), (PG8_LAS unsigned*)(lds + (bufoff) + ldsw + _i * 8192), 16, 0, 0); } while (0)
; #define PG8_LDA(dst, b, h) do { _Pragma("unroll") for (int m = 0; m < 4; ++m) _Pragma("unroll") for (int k = 0; k < 2; ++k) dst[m][k] = *(const PG8_LAS bf16x8*)(lds + PG8_SA(b, h) + aoff + m * 2048 + k * 1024); } while (0)
; #define PG8_WAIT_V(n) asm volatile("s_waitcnt vmcnt(" #n ")" ::: "memory")
; template <class Epi, class Sched, bool ALIGN_EPI = false, bool SP2 = false>
; __device__ __forceinline__ void gemm_phase(PG8_LAS unsigned char* lds, const Gemm g, const Sched& S, const Epi& E) {
;     ...
;             PG8_LDA(At, 1, 1); PG8_STAGE(PG8_SB(1, 0), b3, voffB); PG8_STAGE(PG8_SB(1, 1), b3 + hstep, voffB); PG8_STAGE(PG8_SA(1, 0), a3, voffA);
;             PG8_WAIT_V(8); PG8_WAIT_L(0); PG8_BAR; PG8_MMA(1, 0, At, B0); PG8_MMA(1, 1, At, B1); PG8_BAR; PG8_SCHED;
;             } else {
;             PG8_LDB(B0, 0, 0); PG8_SCHED; PG8_LDA(At, 0, 0); PG8_STAGE(PG8_SA(1, 1), a1 + hstep, voffA);
;             PG8_WAIT_L(8); PG8_BAR; PG8_WAIT_L(0); PG8_MMA(0, 0, At, B0); PG8_BAR; PG8_SCHED;
;             PG8_LDB(B1, 0, 1); PG8_STAGE(PG8_SB(0, 0), b2, voffB);
;             PG8_BAR; PG8_WAIT_L(0); PG8_MMA(0, 1, At, B1); PG8_BAR;
;             PG8_LDA(At, 0, 1); PG8_STAGE(PG8_SA(0, 0), a2, voffA);
;             PG8_BAR; PG8_WAIT_L(0); PG8_MMA(1, 0, At, B0); PG8_BAR; PG8_SCHED;
;             PG8_STAGE(PG8_SB(0, 1), b2 + hstep, voffB);
;             PG8_WAIT_V(6); PG8_BAR; PG8_MMA(1, 1, At, B1); PG8_BAR;
;             PG8_LDB(B0, 1, 0); PG8_SCHED; PG8_LDA(At, 1, 0); PG8_STAGE(PG8_SA(0, 1), a2 + hstep, voffA);
;             PG8_WAIT_L(8); PG8_BAR; PG8_WAIT_L(0); PG8_MMA(0, 0, At, B0); PG8_BAR; PG8_SCHED;
;             PG8_LDB(B1, 1, 1); PG8_STAGE(PG8_SB(1, 0), b3, voffB);
;             PG8_BAR; PG8_WAIT_L(0); PG8_MMA(0, 1, At, B1); PG8_BAR;
;             PG8_LDA(At, 1, 1); PG8_STAGE(PG8_SA(1, 0), a3, voffA);
;             PG8_BAR; PG8_WAIT_L(0); PG8_MMA(1, 0, At, B0); PG8_BAR; PG8_SCHED;
;             PG8_STAGE(PG8_SB(1, 1), b3 + hstep, voffB);
;             PG8_WAIT_V(6); PG8_BAR; PG8_MMA(1, 1, At, B1); PG8_BAR;
;             }
;         }
;         if constexpr (ALIGN_EPI) { if (wr == 0) PG8_BAR; }
	s_add_i32 s46, s93, s63
	v_lshl_add_u64 v[146:147], v[146:147], 0, s[18:19]
	s_mov_b32 m0, s46
	ds_read_b128 v[196:199], v151 offset:49152
	ds_read_b128 v[200:203], v151 offset:50176
	ds_read_b128 v[204:207], v151 offset:51200
	ds_read_b128 v[208:211], v151 offset:52224
	ds_read_b128 v[212:215], v151 offset:53248
	ds_read_b128 v[216:219], v151 offset:54272
	ds_read_b128 v[220:223], v151 offset:55296
	ds_read_b128 v[224:227], v151 offset:56320
	global_load_lds_dwordx4 v[146:147], off
	v_lshl_add_u64 v[146:147], v[182:183], 0, s[18:19]
	s_add_i32 m0, s46, 0x2000
	s_add_i32 s46, s68, s63
	global_load_lds_dwordx4 v[146:147], off
	v_lshl_add_u64 v[146:147], v[184:185], 0, s[18:19]
	v_lshl_add_u64 v[232:233], v[184:185], 0, s[18:19]
	v_lshl_add_u64 v[146:147], v[188:189], 0, s[18:19]
	v_lshl_add_u64 v[234:235], v[188:189], 0, s[18:19]
	v_lshl_add_u64 v[146:147], v[190:191], 0, s[18:19]
	v_lshl_add_u64 v[240:241], v[190:191], 0, s[18:19]
	v_lshl_add_u64 v[146:147], v[228:229], 0, s[18:19]
	v_lshl_add_u64 v[242:243], v[228:229], 0, s[18:19]
	s_waitcnt vmcnt(4)
	s_waitcnt lgkmcnt(0)
	s_barrier
	s_setprio 1
	s_waitcnt lgkmcnt(0)
	v_mfma_f32_16x16x32_bf16 v[60:63], v[138:141], v[196:199], v[60:63]
	s_mov_b32 m0, s46
	v_mfma_f32_16x16x32_bf16 v[56:59], v[156:159], v[196:199], v[56:59]
	global_load_lds_dwordx4 v[232:233], off
	v_mfma_f32_16x16x32_bf16 v[44:47], v[138:141], v[204:207], v[44:47]
	v_mfma_f32_16x16x32_bf16 v[40:43], v[156:159], v[204:207], v[40:43]
	v_mfma_f32_16x16x32_bf16 v[28:31], v[138:141], v[212:215], v[28:31]
	v_mfma_f32_16x16x32_bf16 v[24:27], v[156:159], v[212:215], v[24:27]
	v_mfma_f32_16x16x32_bf16 v[12:15], v[138:141], v[220:223], v[12:15]
	v_mfma_f32_16x16x32_bf16 v[8:11], v[156:159], v[220:223], v[8:11]
	v_mfma_f32_16x16x32_bf16 v[60:63], v[142:145], v[200:203], v[60:63]
	s_add_i32 m0, s46, 0x2000
	v_mfma_f32_16x16x32_bf16 v[56:59], v[160:163], v[200:203], v[56:59]
	global_load_lds_dwordx4 v[234:235], off
	v_mfma_f32_16x16x32_bf16 v[44:47], v[142:145], v[208:211], v[44:47]
	v_mfma_f32_16x16x32_bf16 v[40:43], v[160:163], v[208:211], v[40:43]
	v_mfma_f32_16x16x32_bf16 v[28:31], v[142:145], v[216:219], v[28:31]
	v_mfma_f32_16x16x32_bf16 v[24:27], v[160:163], v[216:219], v[24:27]
	v_mfma_f32_16x16x32_bf16 v[12:15], v[142:145], v[224:227], v[12:15]
	v_mfma_f32_16x16x32_bf16 v[8:11], v[160:163], v[224:227], v[8:11]
	s_setprio 0
	s_setprio 1
	v_mfma_f32_16x16x32_bf16 v[52:55], v[164:167], v[196:199], v[52:55]
	s_mov_b32 m0, s0
	v_mfma_f32_16x16x32_bf16 v[48:51], v[172:175], v[196:199], v[48:51]
	global_load_lds_dwordx4 v[240:241], off
	v_mfma_f32_16x16x32_bf16 v[36:39], v[164:167], v[204:207], v[36:39]
	v_mfma_f32_16x16x32_bf16 v[32:35], v[172:175], v[204:207], v[32:35]
	v_mfma_f32_16x16x32_bf16 v[20:23], v[164:167], v[212:215], v[20:23]
	v_mfma_f32_16x16x32_bf16 v[16:19], v[172:175], v[212:215], v[16:19]
	v_mfma_f32_16x16x32_bf16 v[4:7], v[164:167], v[220:223], v[4:7]
	v_mfma_f32_16x16x32_bf16 v[0:3], v[172:175], v[220:223], v[0:3]
	v_mfma_f32_16x16x32_bf16 v[52:55], v[168:171], v[200:203], v[52:55]
	s_mov_b32 m0, s58
	v_mfma_f32_16x16x32_bf16 v[48:51], v[192:195], v[200:203], v[48:51]
	global_load_lds_dwordx4 v[242:243], off
	v_mfma_f32_16x16x32_bf16 v[36:39], v[168:171], v[208:211], v[36:39]
	v_mfma_f32_16x16x32_bf16 v[32:35], v[192:195], v[208:211], v[32:35]
	v_mfma_f32_16x16x32_bf16 v[20:23], v[168:171], v[216:219], v[20:23]
	v_mfma_f32_16x16x32_bf16 v[16:19], v[192:195], v[216:219], v[16:19]
	v_mfma_f32_16x16x32_bf16 v[4:7], v[168:171], v[224:227], v[4:7]
	v_mfma_f32_16x16x32_bf16 v[0:3], v[192:195], v[224:227], v[0:3]
	s_setprio 0
	s_barrier
	s_add_u32 s44, s44, 0x100
	s_addc_u32 s45, s45, 0
	s_add_u32 s86, s86, 0x100
	s_addc_u32 s87, s87, 0
	s_cmp_ge_u32 vcc_lo, s14
	s_mov_b32 s46, vcc_lo
	s_cbranch_scc0 .LBB0_218
	s_and_b64 vcc, exec, s[36:37]
	s_cbranch_vccz .LBB0_221
	s_barrier

; #define PG8_STAGE(bufoff, gbase, voff) do { _Pragma("unroll") for (int _i = 0; _i < 2; ++_i) \
;         __builtin_amdgcn_global_load_lds((const unsigned*)((const char*)(gbase) + (voff)[_i]), (PG8_LAS unsigned*)(lds + (bufoff) + ldsw + _i * 8192), 16, 0, 0); } while (0)
; #define PG8_LDA(dst, b, h) do { _Pragma("unroll") for (int m = 0; m < 4; ++m) _Pragma("unroll") for (int k = 0; k < 2; ++k) dst[m][k] = *(const PG8_LAS bf16x8*)(lds + PG8_SA(b, h) + aoff + m * 2048 + k * 1024); } while (0)
; #define PG8_LDB(dst, b, h) do { _Pragma("unroll") for (int n = 0; n < 2; ++n) _Pragma("unroll") for (int k = 0; k < 2; ++k) dst[n][k] = *(const PG8_LAS bf16x8*)(lds + PG8_SB(b, h) + boff + n * 2048 + k * 1024); } while (0)
; #define PG8_MMA(ai, bj, At, Bt) do { __builtin_amdgcn_s_setprio(1); _Pragma("unroll") for (int m = 0; m < 4; ++m) _Pragma("unroll") for (int n = 0; n < 2; ++n) _Pragma("unroll") for (int k = 0; k < 2; ++k) \
;         acc[ai][bj][m][n] = __builtin_amdgcn_mfma_f32_16x16x32_bf16(Bt[n][k], At[m][k], acc[ai][bj][m][n], 0, 0, 0); __builtin_amdgcn_s_setprio(0); } while (0)
; #define PG8_WAIT_V(n) asm volatile("s_waitcnt vmcnt(" #n ")" ::: "memory")
; #define PG8_WAIT_L(n) asm volatile("s_waitcnt lgkmcnt(" #n ")" ::: "memory")
; #define PG8_BAR __builtin_amdgcn_s_barrier()
; #define PG8_SCHED __builtin_amdgcn_sched_barrier(0)
; template <class Epi, class Sched, bool ALIGN_EPI = false, bool SP2 = false>
; __device__ __forceinline__ void gemm_phase(PG8_LAS unsigned char* lds, const Gemm g, const Sched& S, const Epi& E) {
;     ...
;         for (int t = 0; t < nt; t += 2) {
;             const bool last = (t == nt - 2);
;             const char* a1 = cA + (size_t)(t + 1) * kstep;
;             const char* a2 = last ? nA : cA + (size_t)(t + 2) * kstep; const char* b2 = last ? nB : cB + (size_t)(t + 2) * kstep;
;             const char* a3 = a2 + kstep; const char* b3 = b2 + kstep;
;             if (last && has_next) S.a_ready(nxt);
;             if constexpr (SP2) {
;             PG8_LDB(B0, 0, 0); PG8_LDB(B1, 0, 1); PG8_SCHED; PG8_LDA(At, 0, 0); PG8_STAGE(PG8_SA(1, 1), a1 + hstep, voffA);
;             PG8_WAIT_V(8); PG8_WAIT_L(0); PG8_BAR; PG8_MMA(0, 0, At, B0); PG8_MMA(0, 1, At, B1); PG8_BAR; PG8_SCHED;
;             PG8_LDA(At, 0, 1); PG8_STAGE(PG8_SB(0, 0), b2, voffB); PG8_STAGE(PG8_SB(0, 1), b2 + hstep, voffB); PG8_STAGE(PG8_SA(0, 0), a2, voffA);
.LBB0_331:
	s_add_u32 s68, s74, 0xfff80080
	s_addc_u32 s69, s75, -1
	s_add_i32 s82, 0, 0x10000
	s_cmp_eq_u32 s81, 28
	s_cselect_b32 s79, s45, s69
	s_cselect_b32 s78, s59, s68
	v_add_u32_e32 v140, s82, v143
	s_cselect_b32 s77, s43, s80
	s_cselect_b32 s76, s63, s71
	s_add_i32 s68, 0, 0x14000
	ds_read_b128 v[146:149], v140
	ds_read_b128 v[156:159], v140 offset:1024
	ds_read_b128 v[160:163], v140 offset:2048
	ds_read_b128 v[164:167], v140 offset:3072
	v_add_u32_e32 v140, s68, v143
	ds_read_b128 v[168:171], v140
	ds_read_b128 v[172:175], v140 offset:1024
	ds_read_b128 v[192:195], v140 offset:2048
	ds_read_b128 v[196:199], v140 offset:3072
	v_lshl_add_u64 v[140:141], s[74:75], 0, v[136:137]
	s_add_i32 m0, s16, 0xc000
	ds_read_b128 v[200:203], v145
	ds_read_b128 v[204:207], v145 offset:1024
	ds_read_b128 v[208:211], v145 offset:2048
	ds_read_b128 v[212:215], v145 offset:3072
	ds_read_b128 v[216:219], v145 offset:4096
	ds_read_b128 v[220:223], v145 offset:5120
	ds_read_b128 v[224:227], v145 offset:6144
	ds_read_b128 v[228:231], v145 offset:7168
	global_load_lds_dwordx4 v[140:141], off
	v_lshl_add_u64 v[140:141], s[74:75], 0, v[138:139]
	s_add_i32 m0, s16, 0xe000
	s_nop 0
	global_load_lds_dwordx4 v[140:141], off
	s_waitcnt vmcnt(8)
	s_waitcnt lgkmcnt(0)
	s_barrier
	s_setprio 1
	s_waitcnt lgkmcnt(0)
	v_mfma_f32_16x16x32_bf16 v[116:119], v[146:149], v[200:203], v[116:119]
	v_mfma_f32_16x16x32_bf16 v[112:115], v[160:163], v[200:203], v[112:115]
	v_mfma_f32_16x16x32_bf16 v[104:107], v[146:149], v[208:211], v[104:107]
	v_mfma_f32_16x16x32_bf16 v[96:99], v[160:163], v[208:211], v[96:99]
	v_mfma_f32_16x16x32_bf16 v[88:91], v[146:149], v[216:219], v[88:91]
	v_mfma_f32_16x16x32_bf16 v[80:83], v[160:163], v[216:219], v[80:83]
	v_mfma_f32_16x16x32_bf16 v[72:75], v[146:149], v[224:227], v[72:75]
	v_mfma_f32_16x16x32_bf16 v[64:67], v[160:163], v[224:227], v[64:67]
	v_mfma_f32_16x16x32_bf16 v[116:119], v[156:159], v[204:207], v[116:119]
	v_mfma_f32_16x16x32_bf16 v[112:115], v[164:167], v[204:207], v[112:115]
	v_mfma_f32_16x16x32_bf16 v[104:107], v[156:159], v[212:215], v[104:107]
	v_mfma_f32_16x16x32_bf16 v[96:99], v[164:167], v[212:215], v[96:99]
	v_mfma_f32_16x16x32_bf16 v[88:91], v[156:159], v[220:223], v[88:91]
	v_mfma_f32_16x16x32_bf16 v[80:83], v[164:167], v[220:223], v[80:83]
	v_mfma_f32_16x16x32_bf16 v[72:75], v[156:159], v[228:231], v[72:75]
	v_mfma_f32_16x16x32_bf16 v[64:67], v[164:167], v[228:231], v[64:67]
	s_setprio 0
	s_setprio 1
	v_mfma_f32_16x16x32_bf16 v[124:127], v[168:171], v[200:203], v[124:127]
	v_mfma_f32_16x16x32_bf16 v[120:123], v[192:195], v[200:203], v[120:123]
	v_mfma_f32_16x16x32_bf16 v[108:111], v[168:171], v[208:211], v[108:111]
	v_mfma_f32_16x16x32_bf16 v[100:103], v[192:195], v[208:211], v[100:103]
	v_mfma_f32_16x16x32_bf16 v[92:95], v[168:171], v[216:219], v[92:95]
	v_mfma_f32_16x16x32_bf16 v[84:87], v[192:195], v[216:219], v[84:87]
	v_mfma_f32_16x16x32_bf16 v[76:79], v[168:171], v[224:227], v[76:79]
	v_mfma_f32_16x16x32_bf16 v[68:71], v[192:195], v[224:227], v[68:71]
	v_mfma_f32_16x16x32_bf16 v[124:127], v[172:175], v[204:207], v[124:127]
	v_mfma_f32_16x16x32_bf16 v[120:123], v[196:199], v[204:207], v[120:123]
	v_mfma_f32_16x16x32_bf16 v[108:111], v[172:175], v[212:215], v[108:111]
	v_mfma_f32_16x16x32_bf16 v[100:103], v[196:199], v[212:215], v[100:103]
	v_mfma_f32_16x16x32_bf16 v[92:95], v[172:175], v[220:223], v[92:95]
	v_mfma_f32_16x16x32_bf16 v[84:87], v[196:199], v[220:223], v[84:87]
	v_mfma_f32_16x16x32_bf16 v[76:79], v[172:175], v[228:231], v[76:79]
	v_mfma_f32_16x16x32_bf16 v[68:71], v[196:199], v[228:231], v[68:71]
	s_setprio 0
	s_barrier
	s_add_i32 s69, s82, s15
	v_lshl_add_u64 v[140:141], s[76:77], 0, v[152:153]
	s_mov_b32 m0, s69
	ds_read_b128 v[200:203], v145 offset:16384
	ds_read_b128 v[204:207], v145 offset:17408
	ds_read_b128 v[208:211], v145 offset:18432
	ds_read_b128 v[212:215], v145 offset:19456
	ds_read_b128 v[216:219], v145 offset:20480
	ds_read_b128 v[220:223], v145 offset:21504
	ds_read_b128 v[224:227], v145 offset:22528
	ds_read_b128 v[228:231], v145 offset:23552
	global_load_lds_dwordx4 v[140:141], off
	s_add_i32 m0, s69, 0x2000
	s_add_u32 s82, s76, 0x80000
	v_lshl_add_u64 v[150:151], s[76:77], 0, v[128:129]
	s_addc_u32 s83, s77, 0
	s_add_i32 s68, s68, s15
	global_load_lds_dwordx4 v[150:151], off
	v_lshl_add_u64 v[182:183], s[82:83], 0, v[152:153]
	v_lshl_add_u64 v[232:233], s[82:83], 0, v[152:153]
	v_lshl_add_u64 v[184:185], s[78:79], 0, v[130:131]
	v_lshl_add_u64 v[182:183], s[82:83], 0, v[128:129]
	v_lshl_add_u64 v[234:235], s[82:83], 0, v[128:129]
	v_lshl_add_u64 v[182:183], s[78:79], 0, v[132:133]
	v_lshl_add_u64 v[240:241], s[78:79], 0, v[132:133]
	v_lshl_add_u64 v[242:243], v[184:185], 0, 0
	s_waitcnt vmcnt(4)
	s_waitcnt lgkmcnt(0)
	s_barrier
; #define PG8_STAGE(bufoff, gbase, voff) do { _Pragma("unroll") for (int _i = 0; _i < 2; ++_i) \
;         __builtin_amdgcn_global_load_lds((const unsigned*)((const char*)(gbase) + (voff)[_i]), (PG8_LAS unsigned*)(lds + (bufoff) + ldsw + _i * 8192), 16, 0, 0); } while (0)
; #define PG8_LDA(dst, b, h) do { _Pragma("unroll") for (int m = 0; m < 4; ++m) _Pragma("unroll") for (int k = 0; k < 2; ++k) dst[m][k] = *(const PG8_LAS bf16x8*)(lds + PG8_SA(b, h) + aoff + m * 2048 + k * 1024); } while (0)
; #define PG8_LDB(dst, b, h) do { _Pragma("unroll") for (int n = 0; n < 2; ++n) _Pragma("unroll") for (int k = 0; k < 2; ++k) dst[n][k] = *(const PG8_LAS bf16x8*)(lds + PG8_SB(b, h) + boff + n * 2048 + k * 1024); } while (0)
; #define PG8_MMA(ai, bj, At, Bt) do { __builtin_amdgcn_s_setprio(1); _Pragma("unroll") for (int m = 0; m < 4; ++m) _Pragma("unroll") for (int n = 0; n < 2; ++n) _Pragma("unroll") for (int k = 0; k < 2; ++k) \
;         acc[ai][bj][m][n] = __builtin_amdgcn_mfma_f32_16x16x32_bf16(Bt[n][k], At[m][k], acc[ai][bj][m][n], 0, 0, 0); __builtin_amdgcn_s_setprio(0); } while (0)
; #define PG8_WAIT_V(n) asm volatile("s_waitcnt vmcnt(" #n ")" ::: "memory")
; #define PG8_WAIT_L(n) asm volatile("s_waitcnt lgkmcnt(" #n ")" ::: "memory")
; #define PG8_BAR __builtin_amdgcn_s_barrier()
; #define PG8_SCHED __builtin_amdgcn_sched_barrier(0)
; template <class Epi, class Sched, bool ALIGN_EPI = false, bool SP2 = false>
; __device__ __forceinline__ void gemm_phase(PG8_LAS unsigned char* lds, const Gemm g, const Sched& S, const Epi& E) {
;     ...
;             PG8_LDA(At, 0, 1); PG8_STAGE(PG8_SB(0, 0), b2, voffB); PG8_STAGE(PG8_SB(0, 1), b2 + hstep, voffB); PG8_STAGE(PG8_SA(0, 0), a2, voffA);
;             PG8_WAIT_V(8); PG8_WAIT_L(0); PG8_BAR; PG8_MMA(1, 0, At, B0); PG8_MMA(1, 1, At, B1); PG8_BAR; PG8_SCHED;
;             PG8_LDB(B0, 1, 0); PG8_LDB(B1, 1, 1); PG8_SCHED; PG8_LDA(At, 1, 0); PG8_STAGE(PG8_SA(0, 1), a2 + hstep, voffA);
;             PG8_WAIT_V(8); PG8_WAIT_L(0); PG8_BAR; PG8_MMA(0, 0, At, B0); PG8_MMA(0, 1, At, B1); PG8_BAR; PG8_SCHED;
	s_setprio 1
	s_waitcnt lgkmcnt(0)
	v_mfma_f32_16x16x32_bf16 v[56:59], v[146:149], v[200:203], v[56:59]
	s_mov_b32 m0, s68
	v_mfma_f32_16x16x32_bf16 v[48:51], v[160:163], v[200:203], v[48:51]
	global_load_lds_dwordx4 v[232:233], off
	v_mfma_f32_16x16x32_bf16 v[40:43], v[146:149], v[208:211], v[40:43]
	v_mfma_f32_16x16x32_bf16 v[32:35], v[160:163], v[208:211], v[32:35]
	v_mfma_f32_16x16x32_bf16 v[24:27], v[146:149], v[216:219], v[24:27]
	v_mfma_f32_16x16x32_bf16 v[16:19], v[160:163], v[216:219], v[16:19]
	v_mfma_f32_16x16x32_bf16 v[8:11], v[146:149], v[224:227], v[8:11]
	v_mfma_f32_16x16x32_bf16 v[4:7], v[160:163], v[224:227], v[4:7]
	v_mfma_f32_16x16x32_bf16 v[56:59], v[156:159], v[204:207], v[56:59]
	s_add_i32 m0, s68, 0x2000
	v_mfma_f32_16x16x32_bf16 v[48:51], v[164:167], v[204:207], v[48:51]
	global_load_lds_dwordx4 v[234:235], off
	v_mfma_f32_16x16x32_bf16 v[40:43], v[156:159], v[212:215], v[40:43]
	v_mfma_f32_16x16x32_bf16 v[32:35], v[164:167], v[212:215], v[32:35]
	v_mfma_f32_16x16x32_bf16 v[24:27], v[156:159], v[220:223], v[24:27]
	v_mfma_f32_16x16x32_bf16 v[16:19], v[164:167], v[220:223], v[16:19]
	v_mfma_f32_16x16x32_bf16 v[8:11], v[156:159], v[228:231], v[8:11]
	v_mfma_f32_16x16x32_bf16 v[4:7], v[164:167], v[228:231], v[4:7]
	s_setprio 0
	s_setprio 1
	v_mfma_f32_16x16x32_bf16 v[60:63], v[168:171], v[200:203], v[60:63]
	s_mov_b32 m0, s16
	v_mfma_f32_16x16x32_bf16 v[52:55], v[192:195], v[200:203], v[52:55]
	global_load_lds_dwordx4 v[240:241], off
	v_mfma_f32_16x16x32_bf16 v[44:47], v[168:171], v[208:211], v[44:47]
	v_mfma_f32_16x16x32_bf16 v[36:39], v[192:195], v[208:211], v[36:39]
	v_mfma_f32_16x16x32_bf16 v[28:31], v[168:171], v[216:219], v[28:31]
	v_mfma_f32_16x16x32_bf16 v[20:23], v[192:195], v[216:219], v[20:23]
	v_mfma_f32_16x16x32_bf16 v[12:15], v[168:171], v[224:227], v[12:15]
	v_mfma_f32_16x16x32_bf16 v[0:3], v[192:195], v[224:227], v[0:3]
	v_mfma_f32_16x16x32_bf16 v[60:63], v[172:175], v[204:207], v[60:63]
	s_mov_b32 m0, s17
	v_mfma_f32_16x16x32_bf16 v[52:55], v[196:199], v[204:207], v[52:55]
	global_load_lds_dwordx4 v[242:243], off
	v_mfma_f32_16x16x32_bf16 v[44:47], v[172:175], v[212:215], v[44:47]
	v_mfma_f32_16x16x32_bf16 v[36:39], v[196:199], v[212:215], v[36:39]
	v_mfma_f32_16x16x32_bf16 v[28:31], v[172:175], v[220:223], v[28:31]
	v_mfma_f32_16x16x32_bf16 v[20:23], v[196:199], v[220:223], v[20:23]
	v_mfma_f32_16x16x32_bf16 v[12:15], v[172:175], v[228:231], v[12:15]
	v_mfma_f32_16x16x32_bf16 v[0:3], v[196:199], v[228:231], v[0:3]
	s_setprio 0
	s_barrier
	v_add_u32_e32 v155, s93, v143
	s_add_i32 s68, 0, 0x1c000
	ds_read_b128 v[146:149], v155
	ds_read_b128 v[156:159], v155 offset:1024
	ds_read_b128 v[160:163], v155 offset:2048
	ds_read_b128 v[164:167], v155 offset:3072
	v_add_u32_e32 v155, s68, v143
	ds_read_b128 v[168:171], v155
	ds_read_b128 v[172:175], v155 offset:1024
	ds_read_b128 v[192:195], v155 offset:2048
	ds_read_b128 v[196:199], v155 offset:3072
	s_add_u32 s78, s78, 0x80000
	s_addc_u32 s79, s79, 0
	s_mov_b32 m0, s22
	v_lshl_add_u64 v[188:189], s[78:79], 0, v[132:133]
	ds_read_b128 v[200:203], v145 offset:32768
	ds_read_b128 v[204:207], v145 offset:33792
	ds_read_b128 v[208:211], v145 offset:34816
	ds_read_b128 v[212:215], v145 offset:35840
	ds_read_b128 v[216:219], v145 offset:36864
	ds_read_b128 v[220:223], v145 offset:37888
	ds_read_b128 v[224:227], v145 offset:38912
	ds_read_b128 v[228:231], v145 offset:39936
	global_load_lds_dwordx4 v[188:189], off
	v_lshl_add_u64 v[188:189], s[78:79], 0, v[130:131]
	s_mov_b32 m0, s23
	s_nop 0
	global_load_lds_dwordx4 v[188:189], off
	s_waitcnt vmcnt(8)
	s_waitcnt lgkmcnt(0)
	s_barrier
	s_setprio 1
	s_waitcnt lgkmcnt(0)
	v_mfma_f32_16x16x32_bf16 v[116:119], v[146:149], v[200:203], v[116:119]
	v_mfma_f32_16x16x32_bf16 v[112:115], v[160:163], v[200:203], v[112:115]
	v_mfma_f32_16x16x32_bf16 v[104:107], v[146:149], v[208:211], v[104:107]
	v_mfma_f32_16x16x32_bf16 v[96:99], v[160:163], v[208:211], v[96:99]
	v_mfma_f32_16x16x32_bf16 v[88:91], v[146:149], v[216:219], v[88:91]
	v_mfma_f32_16x16x32_bf16 v[80:83], v[160:163], v[216:219], v[80:83]
	v_mfma_f32_16x16x32_bf16 v[72:75], v[146:149], v[224:227], v[72:75]
	v_mfma_f32_16x16x32_bf16 v[64:67], v[160:163], v[224:227], v[64:67]
	v_mfma_f32_16x16x32_bf16 v[116:119], v[156:159], v[204:207], v[116:119]
	v_mfma_f32_16x16x32_bf16 v[112:115], v[164:167], v[204:207], v[112:115]
	v_mfma_f32_16x16x32_bf16 v[104:107], v[156:159], v[212:215], v[104:107]
	v_mfma_f32_16x16x32_bf16 v[96:99], v[164:167], v[212:215], v[96:99]
	v_mfma_f32_16x16x32_bf16 v[88:91], v[156:159], v[220:223], v[88:91]
	v_mfma_f32_16x16x32_bf16 v[80:83], v[164:167], v[220:223], v[80:83]
	v_mfma_f32_16x16x32_bf16 v[72:75], v[156:159], v[228:231], v[72:75]
	v_mfma_f32_16x16x32_bf16 v[64:67], v[164:167], v[228:231], v[64:67]
	s_setprio 0
	s_setprio 1
	v_mfma_f32_16x16x32_bf16 v[124:127], v[168:171], v[200:203], v[124:127]
	v_mfma_f32_16x16x32_bf16 v[120:123], v[192:195], v[200:203], v[120:123]
	v_mfma_f32_16x16x32_bf16 v[108:111], v[168:171], v[208:211], v[108:111]
	v_mfma_f32_16x16x32_bf16 v[100:103], v[192:195], v[208:211], v[100:103]
	v_mfma_f32_16x16x32_bf16 v[92:95], v[168:171], v[216:219], v[92:95]
	v_mfma_f32_16x16x32_bf16 v[84:87], v[192:195], v[216:219], v[84:87]
	v_mfma_f32_16x16x32_bf16 v[76:79], v[168:171], v[224:227], v[76:79]
	v_mfma_f32_16x16x32_bf16 v[68:71], v[192:195], v[224:227], v[68:71]
	v_mfma_f32_16x16x32_bf16 v[124:127], v[172:175], v[204:207], v[124:127]
	v_mfma_f32_16x16x32_bf16 v[120:123], v[196:199], v[204:207], v[120:123]
	v_mfma_f32_16x16x32_bf16 v[108:111], v[172:175], v[212:215], v[108:111]
	v_mfma_f32_16x16x32_bf16 v[100:103], v[196:199], v[212:215], v[100:103]
	v_mfma_f32_16x16x32_bf16 v[92:95], v[172:175], v[220:223], v[92:95]
	v_mfma_f32_16x16x32_bf16 v[84:87], v[196:199], v[220:223], v[84:87]
	v_mfma_f32_16x16x32_bf16 v[76:79], v[172:175], v[228:231], v[76:79]
	v_mfma_f32_16x16x32_bf16 v[68:71], v[196:199], v[228:231], v[68:71]
	s_setprio 0
	s_barrier
; #define PG8_STAGE(bufoff, gbase, voff) do { _Pragma("unroll") for (int _i = 0; _i < 2; ++_i) \
;         __builtin_amdgcn_global_load_lds((const unsigned*)((const char*)(gbase) + (voff)[_i]), (PG8_LAS unsigned*)(lds + (bufoff) + ldsw + _i * 8192), 16, 0, 0); } while (0)
; #define PG8_LDA(dst, b, h) do { _Pragma("unroll") for (int m = 0; m < 4; ++m) _Pragma("unroll") for (int k = 0; k < 2; ++k) dst[m][k] = *(const PG8_LAS bf16x8*)(lds + PG8_SA(b, h) + aoff + m * 2048 + k * 1024); } while (0)
; #define PG8_WAIT_V(n) asm volatile("s_waitcnt vmcnt(" #n ")" ::: "memory")
; template <class Epi, class Sched, bool ALIGN_EPI = false, bool SP2 = false>
; __device__ __forceinline__ void gemm_phase(PG8_LAS unsigned char* lds, const Gemm g, const Sched& S, const Epi& E) {
;     ...
;             PG8_LDA(At, 1, 1); PG8_STAGE(PG8_SB(1, 0), b3, voffB); PG8_STAGE(PG8_SB(1, 1), b3 + hstep, voffB); PG8_STAGE(PG8_SA(1, 0), a3, voffA);
;             PG8_WAIT_V(8); PG8_WAIT_L(0); PG8_BAR; PG8_MMA(1, 0, At, B0); PG8_MMA(1, 1, At, B1); PG8_BAR; PG8_SCHED;
;             } else {
;             PG8_LDB(B0, 0, 0); PG8_SCHED; PG8_LDA(At, 0, 0); PG8_STAGE(PG8_SA(1, 1), a1 + hstep, voffA);
;             PG8_WAIT_L(8); PG8_BAR; PG8_WAIT_L(0); PG8_MMA(0, 0, At, B0); PG8_BAR; PG8_SCHED;
;             PG8_LDB(B1, 0, 1); PG8_STAGE(PG8_SB(0, 0), b2, voffB);
;             PG8_BAR; PG8_WAIT_L(0); PG8_MMA(0, 1, At, B1); PG8_BAR;
;             PG8_LDA(At, 0, 1); PG8_STAGE(PG8_SA(0, 0), a2, voffA);
;             PG8_BAR; PG8_WAIT_L(0); PG8_MMA(1, 0, At, B0); PG8_BAR; PG8_SCHED;
;             PG8_STAGE(PG8_SB(0, 1), b2 + hstep, voffB);
;             PG8_WAIT_V(6); PG8_BAR; PG8_MMA(1, 1, At, B1); PG8_BAR;
;             PG8_LDB(B0, 1, 0); PG8_SCHED; PG8_LDA(At, 1, 0); PG8_STAGE(PG8_SA(0, 1), a2 + hstep, voffA);
;             PG8_WAIT_L(8); PG8_BAR; PG8_WAIT_L(0); PG8_MMA(0, 0, At, B0); PG8_BAR; PG8_SCHED;
;             PG8_LDB(B1, 1, 1); PG8_STAGE(PG8_SB(1, 0), b3, voffB);
;             PG8_BAR; PG8_WAIT_L(0); PG8_MMA(0, 1, At, B1); PG8_BAR;
;             PG8_LDA(At, 1, 1); PG8_STAGE(PG8_SA(1, 0), a3, voffA);
;             PG8_BAR; PG8_WAIT_L(0); PG8_MMA(1, 0, At, B0); PG8_BAR; PG8_SCHED;
;             PG8_STAGE(PG8_SB(1, 1), b3 + hstep, voffB);
;             PG8_WAIT_V(6); PG8_BAR; PG8_MMA(1, 1, At, B1); PG8_BAR;
;             }
;         }
;         if constexpr (ALIGN_EPI) { if (wr == 0) PG8_BAR; }
	s_add_i32 s69, s93, s15
	v_lshl_add_u64 v[140:141], v[140:141], 0, s[18:19]
	s_mov_b32 m0, s69
	ds_read_b128 v[200:203], v145 offset:49152
	ds_read_b128 v[204:207], v145 offset:50176
	ds_read_b128 v[208:211], v145 offset:51200
	ds_read_b128 v[212:215], v145 offset:52224
	ds_read_b128 v[216:219], v145 offset:53248
	ds_read_b128 v[220:223], v145 offset:54272
	ds_read_b128 v[224:227], v145 offset:55296
	ds_read_b128 v[228:231], v145 offset:56320
	global_load_lds_dwordx4 v[140:141], off
	s_add_i32 m0, s69, 0x2000
	s_add_u32 s76, s76, 0x80080
	v_lshl_add_u64 v[140:141], v[150:151], 0, s[18:19]
	s_addc_u32 s77, s77, 0
	s_add_i32 s68, s68, s15
	global_load_lds_dwordx4 v[140:141], off
	v_lshl_add_u64 v[140:141], s[76:77], 0, v[152:153]
	v_lshl_add_u64 v[232:233], s[76:77], 0, v[152:153]
	v_lshl_add_u64 v[140:141], s[76:77], 0, v[128:129]
	v_lshl_add_u64 v[234:235], s[76:77], 0, v[128:129]
	v_lshl_add_u64 v[140:141], v[182:183], 0, s[18:19]
	v_lshl_add_u64 v[240:241], v[182:183], 0, s[18:19]
	v_lshl_add_u64 v[140:141], v[184:185], 0, s[18:19]
	v_lshl_add_u64 v[242:243], v[184:185], 0, s[18:19]
	s_waitcnt vmcnt(4)
	s_waitcnt lgkmcnt(0)
	s_barrier
	s_setprio 1
	s_waitcnt lgkmcnt(0)
	v_mfma_f32_16x16x32_bf16 v[56:59], v[146:149], v[200:203], v[56:59]
	s_mov_b32 m0, s68
	v_mfma_f32_16x16x32_bf16 v[48:51], v[160:163], v[200:203], v[48:51]
	global_load_lds_dwordx4 v[232:233], off
	v_mfma_f32_16x16x32_bf16 v[40:43], v[146:149], v[208:211], v[40:43]
	v_mfma_f32_16x16x32_bf16 v[32:35], v[160:163], v[208:211], v[32:35]
	v_mfma_f32_16x16x32_bf16 v[24:27], v[146:149], v[216:219], v[24:27]
	v_mfma_f32_16x16x32_bf16 v[16:19], v[160:163], v[216:219], v[16:19]
	v_mfma_f32_16x16x32_bf16 v[8:11], v[146:149], v[224:227], v[8:11]
	v_mfma_f32_16x16x32_bf16 v[4:7], v[160:163], v[224:227], v[4:7]
	v_mfma_f32_16x16x32_bf16 v[56:59], v[156:159], v[204:207], v[56:59]
	s_add_i32 m0, s68, 0x2000
	v_mfma_f32_16x16x32_bf16 v[48:51], v[164:167], v[204:207], v[48:51]
	global_load_lds_dwordx4 v[234:235], off
	v_mfma_f32_16x16x32_bf16 v[40:43], v[156:159], v[212:215], v[40:43]
	v_mfma_f32_16x16x32_bf16 v[32:35], v[164:167], v[212:215], v[32:35]
	v_mfma_f32_16x16x32_bf16 v[24:27], v[156:159], v[220:223], v[24:27]
	v_mfma_f32_16x16x32_bf16 v[16:19], v[164:167], v[220:223], v[16:19]
	v_mfma_f32_16x16x32_bf16 v[8:11], v[156:159], v[228:231], v[8:11]
	v_mfma_f32_16x16x32_bf16 v[4:7], v[164:167], v[228:231], v[4:7]
	s_setprio 0
	s_setprio 1
	v_mfma_f32_16x16x32_bf16 v[60:63], v[168:171], v[200:203], v[60:63]
	s_mov_b32 m0, s26
	v_mfma_f32_16x16x32_bf16 v[52:55], v[192:195], v[200:203], v[52:55]
	global_load_lds_dwordx4 v[240:241], off
	v_mfma_f32_16x16x32_bf16 v[44:47], v[168:171], v[208:211], v[44:47]
	v_mfma_f32_16x16x32_bf16 v[36:39], v[192:195], v[208:211], v[36:39]
	v_mfma_f32_16x16x32_bf16 v[28:31], v[168:171], v[216:219], v[28:31]
	v_mfma_f32_16x16x32_bf16 v[20:23], v[192:195], v[216:219], v[20:23]
	v_mfma_f32_16x16x32_bf16 v[12:15], v[168:171], v[224:227], v[12:15]
	v_mfma_f32_16x16x32_bf16 v[0:3], v[192:195], v[224:227], v[0:3]
	v_mfma_f32_16x16x32_bf16 v[60:63], v[172:175], v[204:207], v[60:63]
	s_mov_b32 m0, s34
	v_mfma_f32_16x16x32_bf16 v[52:55], v[196:199], v[204:207], v[52:55]
	global_load_lds_dwordx4 v[242:243], off
	v_mfma_f32_16x16x32_bf16 v[44:47], v[172:175], v[212:215], v[44:47]
	v_mfma_f32_16x16x32_bf16 v[36:39], v[196:199], v[212:215], v[36:39]
	v_mfma_f32_16x16x32_bf16 v[28:31], v[172:175], v[220:223], v[28:31]
	v_mfma_f32_16x16x32_bf16 v[20:23], v[196:199], v[220:223], v[20:23]
	v_mfma_f32_16x16x32_bf16 v[12:15], v[172:175], v[228:231], v[12:15]
	v_mfma_f32_16x16x32_bf16 v[0:3], v[196:199], v[228:231], v[0:3]
	s_setprio 0
	s_barrier
	s_add_i32 s81, s81, 2
	s_add_u32 s74, s74, 0x100
	s_addc_u32 s75, s75, 0
	s_add_u32 s71, s71, 0x100
	s_addc_u32 s80, s80, 0
	s_cmp_gt_u32 s81, 29
	s_cbranch_scc0 .LBB0_331
	s_and_b64 vcc, exec, s[36:37]
	s_cbranch_vccz .LBB0_334
	s_barrier

; #define PG8_STAGE(bufoff, gbase, voff) do { _Pragma("unroll") for (int _i = 0; _i < 2; ++_i) \
;         __builtin_amdgcn_global_load_lds((const unsigned*)((const char*)(gbase) + (voff)[_i]), (PG8_LAS unsigned*)(lds + (bufoff) + ldsw + _i * 8192), 16, 0, 0); } while (0)
; #define PG8_LDA(dst, b, h) do { _Pragma("unroll") for (int m = 0; m < 4; ++m) _Pragma("unroll") for (int k = 0; k < 2; ++k) dst[m][k] = *(const PG8_LAS bf16x8*)(lds + PG8_SA(b, h) + aoff + m * 2048 + k * 1024); } while (0)
; #define PG8_LDB(dst, b, h) do { _Pragma("unroll") for (int n = 0; n < 2; ++n) _Pragma("unroll") for (int k = 0; k < 2; ++k) dst[n][k] = *(const PG8_LAS bf16x8*)(lds + PG8_SB(b, h) + boff + n * 2048 + k * 1024); } while (0)
; #define PG8_MMA(ai, bj, At, Bt) do { __builtin_amdgcn_s_setprio(1); _Pragma("unroll") for (int m = 0; m < 4; ++m) _Pragma("unroll") for (int n = 0; n < 2; ++n) _Pragma("unroll") for (int k = 0; k < 2; ++k) \
;         acc[ai][bj][m][n] = __builtin_amdgcn_mfma_f32_16x16x32_bf16(Bt[n][k], At[m][k], acc[ai][bj][m][n], 0, 0, 0); __builtin_amdgcn_s_setprio(0); } while (0)
; #define PG8_WAIT_V(n) asm volatile("s_waitcnt vmcnt(" #n ")" ::: "memory")
; #define PG8_WAIT_L(n) asm volatile("s_waitcnt lgkmcnt(" #n ")" ::: "memory")
; #define PG8_BAR __builtin_amdgcn_s_barrier()
; #define PG8_SCHED __builtin_amdgcn_sched_barrier(0)
; template <class Epi, class Sched, bool ALIGN_EPI = false, bool SP2 = false>
; __device__ __forceinline__ void gemm_phase(PG8_LAS unsigned char* lds, const Gemm g, const Sched& S, const Epi& E) {
;     ...
;             const bool last = (t == nt - 2);
;             const char* a1 = cA + (size_t)(t + 1) * kstep;
;             const char* a2 = last ? nA : cA + (size_t)(t + 2) * kstep; const char* b2 = last ? nB : cB + (size_t)(t + 2) * kstep;
;             const char* a3 = a2 + kstep; const char* b3 = b2 + kstep;
;             if (last && has_next) S.a_ready(nxt);
;             if constexpr (SP2) {
;             PG8_LDB(B0, 0, 0); PG8_LDB(B1, 0, 1); PG8_SCHED; PG8_LDA(At, 0, 0); PG8_STAGE(PG8_SA(1, 1), a1 + hstep, voffA);
;             PG8_WAIT_V(8); PG8_WAIT_L(0); PG8_BAR; PG8_MMA(0, 0, At, B0); PG8_MMA(0, 1, At, B1); PG8_BAR; PG8_SCHED;
;             PG8_LDA(At, 0, 1); PG8_STAGE(PG8_SB(0, 0), b2, voffB); PG8_STAGE(PG8_SB(0, 1), b2 + hstep, voffB); PG8_STAGE(PG8_SA(0, 0), a2, voffA);
.LBB0_354:
	s_add_u32 s68, s48, 0xfff80080
	s_addc_u32 s69, s49, -1
	s_add_i32 s78, 0, 0x10000
	s_cmp_eq_u32 s71, 28
	s_cselect_b32 s77, s41, s69
	s_cselect_b32 s76, s55, s68
	v_add_u32_e32 v150, s78, v139
	s_cselect_b32 s75, s39, s63
	s_cselect_b32 s74, s58, s59
	s_add_i32 s68, 0, 0x14000
	ds_read_b128 v[142:145], v150
	ds_read_b128 v[146:149], v150 offset:1024
	ds_read_b128 v[156:159], v150 offset:2048
	ds_read_b128 v[160:163], v150 offset:3072
	v_add_u32_e32 v150, s68, v139
	ds_read_b128 v[164:167], v150
	ds_read_b128 v[168:171], v150 offset:1024
	ds_read_b128 v[172:175], v150 offset:2048
	ds_read_b128 v[192:195], v150 offset:3072
	v_lshl_add_u64 v[150:151], s[48:49], 0, v[134:135]
	s_add_i32 m0, s16, 0xc000
	ds_read_b128 v[196:199], v141
	ds_read_b128 v[200:203], v141 offset:1024
	ds_read_b128 v[204:207], v141 offset:2048
	ds_read_b128 v[208:211], v141 offset:3072
	ds_read_b128 v[212:215], v141 offset:4096
	ds_read_b128 v[216:219], v141 offset:5120
	ds_read_b128 v[220:223], v141 offset:6144
	ds_read_b128 v[224:227], v141 offset:7168
	global_load_lds_dwordx4 v[150:151], off
	v_lshl_add_u64 v[150:151], s[48:49], 0, v[136:137]
	s_add_i32 m0, s16, 0xe000
	s_nop 0
	global_load_lds_dwordx4 v[150:151], off
	s_waitcnt vmcnt(8)
	s_waitcnt lgkmcnt(0)
	s_barrier
	s_setprio 1
	s_waitcnt lgkmcnt(0)
	v_mfma_f32_16x16x32_bf16 v[124:127], v[142:145], v[196:199], v[124:127]
	v_mfma_f32_16x16x32_bf16 v[120:123], v[156:159], v[196:199], v[120:123]
	v_mfma_f32_16x16x32_bf16 v[116:119], v[142:145], v[204:207], v[116:119]
	v_mfma_f32_16x16x32_bf16 v[108:111], v[156:159], v[204:207], v[108:111]
	v_mfma_f32_16x16x32_bf16 v[100:103], v[142:145], v[212:215], v[100:103]
	v_mfma_f32_16x16x32_bf16 v[92:95], v[156:159], v[212:215], v[92:95]
	v_mfma_f32_16x16x32_bf16 v[84:87], v[142:145], v[220:223], v[84:87]
	v_mfma_f32_16x16x32_bf16 v[76:79], v[156:159], v[220:223], v[76:79]
	v_mfma_f32_16x16x32_bf16 v[124:127], v[146:149], v[200:203], v[124:127]
	v_mfma_f32_16x16x32_bf16 v[120:123], v[160:163], v[200:203], v[120:123]
	v_mfma_f32_16x16x32_bf16 v[116:119], v[146:149], v[208:211], v[116:119]
	v_mfma_f32_16x16x32_bf16 v[108:111], v[160:163], v[208:211], v[108:111]
	v_mfma_f32_16x16x32_bf16 v[100:103], v[146:149], v[216:219], v[100:103]
	v_mfma_f32_16x16x32_bf16 v[92:95], v[160:163], v[216:219], v[92:95]
	v_mfma_f32_16x16x32_bf16 v[84:87], v[146:149], v[224:227], v[84:87]
	v_mfma_f32_16x16x32_bf16 v[76:79], v[160:163], v[224:227], v[76:79]
	s_setprio 0
	s_setprio 1
	v_mfma_f32_16x16x32_bf16 v[112:115], v[164:167], v[196:199], v[112:115]
	v_mfma_f32_16x16x32_bf16 v[104:107], v[172:175], v[196:199], v[104:107]
	v_mfma_f32_16x16x32_bf16 v[96:99], v[164:167], v[204:207], v[96:99]
	v_mfma_f32_16x16x32_bf16 v[88:91], v[172:175], v[204:207], v[88:91]
	v_mfma_f32_16x16x32_bf16 v[80:83], v[164:167], v[212:215], v[80:83]
	v_mfma_f32_16x16x32_bf16 v[72:75], v[172:175], v[212:215], v[72:75]
	v_mfma_f32_16x16x32_bf16 v[68:71], v[164:167], v[220:223], v[68:71]
	v_mfma_f32_16x16x32_bf16 v[64:67], v[172:175], v[220:223], v[64:67]
	v_mfma_f32_16x16x32_bf16 v[112:115], v[168:171], v[200:203], v[112:115]
	v_mfma_f32_16x16x32_bf16 v[104:107], v[192:195], v[200:203], v[104:107]
	v_mfma_f32_16x16x32_bf16 v[96:99], v[168:171], v[208:211], v[96:99]
	v_mfma_f32_16x16x32_bf16 v[88:91], v[192:195], v[208:211], v[88:91]
	v_mfma_f32_16x16x32_bf16 v[80:83], v[168:171], v[216:219], v[80:83]
	v_mfma_f32_16x16x32_bf16 v[72:75], v[192:195], v[216:219], v[72:75]
	v_mfma_f32_16x16x32_bf16 v[68:71], v[168:171], v[224:227], v[68:71]
	v_mfma_f32_16x16x32_bf16 v[64:67], v[192:195], v[224:227], v[64:67]
	s_setprio 0
	s_barrier
	s_add_i32 s69, s78, s0
	v_lshl_add_u64 v[150:151], s[74:75], 0, v[152:153]
	s_mov_b32 m0, s69
	ds_read_b128 v[196:199], v141 offset:16384
	ds_read_b128 v[200:203], v141 offset:17408
	ds_read_b128 v[204:207], v141 offset:18432
	ds_read_b128 v[208:211], v141 offset:19456
	ds_read_b128 v[212:215], v141 offset:20480
	ds_read_b128 v[216:219], v141 offset:21504
	ds_read_b128 v[220:223], v141 offset:22528
	ds_read_b128 v[224:227], v141 offset:23552
	global_load_lds_dwordx4 v[150:151], off
	s_add_i32 m0, s69, 0x2000
	s_add_u32 s78, s74, 0x80000
	v_lshl_add_u64 v[182:183], s[74:75], 0, v[132:133]
	s_addc_u32 s79, s75, 0
	s_add_i32 s68, s68, s0
	global_load_lds_dwordx4 v[182:183], off
	v_lshl_add_u64 v[184:185], s[78:79], 0, v[152:153]
	v_lshl_add_u64 v[232:233], s[78:79], 0, v[152:153]
	v_lshl_add_u64 v[188:189], s[76:77], 0, v[130:131]
	v_lshl_add_u64 v[184:185], s[78:79], 0, v[132:133]
	v_lshl_add_u64 v[234:235], s[78:79], 0, v[132:133]
	v_lshl_add_u64 v[184:185], s[76:77], 0, v[128:129]
	v_lshl_add_u64 v[240:241], s[76:77], 0, v[128:129]
	v_lshl_add_u64 v[242:243], v[188:189], 0, 0
	s_waitcnt vmcnt(4)
	s_waitcnt lgkmcnt(0)
	s_barrier
; #define PG8_STAGE(bufoff, gbase, voff) do { _Pragma("unroll") for (int _i = 0; _i < 2; ++_i) \
;         __builtin_amdgcn_global_load_lds((const unsigned*)((const char*)(gbase) + (voff)[_i]), (PG8_LAS unsigned*)(lds + (bufoff) + ldsw + _i * 8192), 16, 0, 0); } while (0)
; #define PG8_LDA(dst, b, h) do { _Pragma("unroll") for (int m = 0; m < 4; ++m) _Pragma("unroll") for (int k = 0; k < 2; ++k) dst[m][k] = *(const PG8_LAS bf16x8*)(lds + PG8_SA(b, h) + aoff + m * 2048 + k * 1024); } while (0)
; #define PG8_LDB(dst, b, h) do { _Pragma("unroll") for (int n = 0; n < 2; ++n) _Pragma("unroll") for (int k = 0; k < 2; ++k) dst[n][k] = *(const PG8_LAS bf16x8*)(lds + PG8_SB(b, h) + boff + n * 2048 + k * 1024); } while (0)
; #define PG8_MMA(ai, bj, At, Bt) do { __builtin_amdgcn_s_setprio(1); _Pragma("unroll") for (int m = 0; m < 4; ++m) _Pragma("unroll") for (int n = 0; n < 2; ++n) _Pragma("unroll") for (int k = 0; k < 2; ++k) \
;         acc[ai][bj][m][n] = __builtin_amdgcn_mfma_f32_16x16x32_bf16(Bt[n][k], At[m][k], acc[ai][bj][m][n], 0, 0, 0); __builtin_amdgcn_s_setprio(0); } while (0)
; #define PG8_WAIT_V(n) asm volatile("s_waitcnt vmcnt(" #n ")" ::: "memory")
; #define PG8_WAIT_L(n) asm volatile("s_waitcnt lgkmcnt(" #n ")" ::: "memory")
; #define PG8_BAR __builtin_amdgcn_s_barrier()
; #define PG8_SCHED __builtin_amdgcn_sched_barrier(0)
; template <class Epi, class Sched, bool ALIGN_EPI = false, bool SP2 = false>
; __device__ __forceinline__ void gemm_phase(PG8_LAS unsigned char* lds, const Gemm g, const Sched& S, const Epi& E) {
;     ...
;             PG8_WAIT_V(8); PG8_WAIT_L(0); PG8_BAR; PG8_MMA(1, 0, At, B0); PG8_MMA(1, 1, At, B1); PG8_BAR; PG8_SCHED;
;             PG8_LDB(B0, 1, 0); PG8_LDB(B1, 1, 1); PG8_SCHED; PG8_LDA(At, 1, 0); PG8_STAGE(PG8_SA(0, 1), a2 + hstep, voffA);
;             PG8_WAIT_V(8); PG8_WAIT_L(0); PG8_BAR; PG8_MMA(0, 0, At, B0); PG8_MMA(0, 1, At, B1); PG8_BAR; PG8_SCHED;
	s_setprio 1
	s_waitcnt lgkmcnt(0)
	v_mfma_f32_16x16x32_bf16 v[60:63], v[142:145], v[196:199], v[60:63]
	s_mov_b32 m0, s68
	v_mfma_f32_16x16x32_bf16 v[56:59], v[156:159], v[196:199], v[56:59]
	global_load_lds_dwordx4 v[232:233], off
	v_mfma_f32_16x16x32_bf16 v[52:55], v[142:145], v[204:207], v[52:55]
	v_mfma_f32_16x16x32_bf16 v[44:47], v[156:159], v[204:207], v[44:47]
	v_mfma_f32_16x16x32_bf16 v[36:39], v[142:145], v[212:215], v[36:39]
	v_mfma_f32_16x16x32_bf16 v[28:31], v[156:159], v[212:215], v[28:31]
	v_mfma_f32_16x16x32_bf16 v[20:23], v[142:145], v[220:223], v[20:23]
	v_mfma_f32_16x16x32_bf16 v[12:15], v[156:159], v[220:223], v[12:15]
	v_mfma_f32_16x16x32_bf16 v[60:63], v[146:149], v[200:203], v[60:63]
	s_add_i32 m0, s68, 0x2000
	v_mfma_f32_16x16x32_bf16 v[56:59], v[160:163], v[200:203], v[56:59]
	global_load_lds_dwordx4 v[234:235], off
	v_mfma_f32_16x16x32_bf16 v[52:55], v[146:149], v[208:211], v[52:55]
	v_mfma_f32_16x16x32_bf16 v[44:47], v[160:163], v[208:211], v[44:47]
	v_mfma_f32_16x16x32_bf16 v[36:39], v[146:149], v[216:219], v[36:39]
	v_mfma_f32_16x16x32_bf16 v[28:31], v[160:163], v[216:219], v[28:31]
	v_mfma_f32_16x16x32_bf16 v[20:23], v[146:149], v[224:227], v[20:23]
	v_mfma_f32_16x16x32_bf16 v[12:15], v[160:163], v[224:227], v[12:15]
	s_setprio 0
	s_setprio 1
	v_mfma_f32_16x16x32_bf16 v[48:51], v[164:167], v[196:199], v[48:51]
	s_mov_b32 m0, s16
	v_mfma_f32_16x16x32_bf16 v[40:43], v[172:175], v[196:199], v[40:43]
	global_load_lds_dwordx4 v[240:241], off
	v_mfma_f32_16x16x32_bf16 v[32:35], v[164:167], v[204:207], v[32:35]
	v_mfma_f32_16x16x32_bf16 v[24:27], v[172:175], v[204:207], v[24:27]
	v_mfma_f32_16x16x32_bf16 v[16:19], v[164:167], v[212:215], v[16:19]
	v_mfma_f32_16x16x32_bf16 v[8:11], v[172:175], v[212:215], v[8:11]
	v_mfma_f32_16x16x32_bf16 v[4:7], v[164:167], v[220:223], v[4:7]
	v_mfma_f32_16x16x32_bf16 v[0:3], v[172:175], v[220:223], v[0:3]
	v_mfma_f32_16x16x32_bf16 v[48:51], v[168:171], v[200:203], v[48:51]
	s_mov_b32 m0, s17
	v_mfma_f32_16x16x32_bf16 v[40:43], v[192:195], v[200:203], v[40:43]
	global_load_lds_dwordx4 v[242:243], off
	v_mfma_f32_16x16x32_bf16 v[32:35], v[168:171], v[208:211], v[32:35]
	v_mfma_f32_16x16x32_bf16 v[24:27], v[192:195], v[208:211], v[24:27]
	v_mfma_f32_16x16x32_bf16 v[16:19], v[168:171], v[216:219], v[16:19]
	v_mfma_f32_16x16x32_bf16 v[8:11], v[192:195], v[216:219], v[8:11]
	v_mfma_f32_16x16x32_bf16 v[4:7], v[168:171], v[224:227], v[4:7]
	v_mfma_f32_16x16x32_bf16 v[0:3], v[192:195], v[224:227], v[0:3]
	s_setprio 0
	s_barrier
	v_add_u32_e32 v155, s93, v139
	s_add_i32 s68, 0, 0x1c000
	ds_read_b128 v[142:145], v155
	ds_read_b128 v[146:149], v155 offset:1024
	ds_read_b128 v[156:159], v155 offset:2048
	ds_read_b128 v[160:163], v155 offset:3072
	v_add_u32_e32 v155, s68, v139
	ds_read_b128 v[164:167], v155
	ds_read_b128 v[168:171], v155 offset:1024
	ds_read_b128 v[172:175], v155 offset:2048
	ds_read_b128 v[192:195], v155 offset:3072
	s_add_u32 s76, s76, 0x80000
	s_addc_u32 s77, s77, 0
	s_mov_b32 m0, s22
	v_lshl_add_u64 v[190:191], s[76:77], 0, v[128:129]
	ds_read_b128 v[196:199], v141 offset:32768
	ds_read_b128 v[200:203], v141 offset:33792
	ds_read_b128 v[204:207], v141 offset:34816
	ds_read_b128 v[208:211], v141 offset:35840
	ds_read_b128 v[212:215], v141 offset:36864
	ds_read_b128 v[216:219], v141 offset:37888
	ds_read_b128 v[220:223], v141 offset:38912
	ds_read_b128 v[224:227], v141 offset:39936
	global_load_lds_dwordx4 v[190:191], off
	v_lshl_add_u64 v[190:191], s[76:77], 0, v[130:131]
	s_mov_b32 m0, s23
	s_nop 0
	global_load_lds_dwordx4 v[190:191], off
	s_waitcnt vmcnt(8)
	s_waitcnt lgkmcnt(0)
	s_barrier
	s_setprio 1
	s_waitcnt lgkmcnt(0)
	v_mfma_f32_16x16x32_bf16 v[124:127], v[142:145], v[196:199], v[124:127]
	v_mfma_f32_16x16x32_bf16 v[120:123], v[156:159], v[196:199], v[120:123]
	v_mfma_f32_16x16x32_bf16 v[116:119], v[142:145], v[204:207], v[116:119]
	v_mfma_f32_16x16x32_bf16 v[108:111], v[156:159], v[204:207], v[108:111]
	v_mfma_f32_16x16x32_bf16 v[100:103], v[142:145], v[212:215], v[100:103]
	v_mfma_f32_16x16x32_bf16 v[92:95], v[156:159], v[212:215], v[92:95]
	v_mfma_f32_16x16x32_bf16 v[84:87], v[142:145], v[220:223], v[84:87]
	v_mfma_f32_16x16x32_bf16 v[76:79], v[156:159], v[220:223], v[76:79]
	v_mfma_f32_16x16x32_bf16 v[124:127], v[146:149], v[200:203], v[124:127]
	v_mfma_f32_16x16x32_bf16 v[120:123], v[160:163], v[200:203], v[120:123]
	v_mfma_f32_16x16x32_bf16 v[116:119], v[146:149], v[208:211], v[116:119]
	v_mfma_f32_16x16x32_bf16 v[108:111], v[160:163], v[208:211], v[108:111]
	v_mfma_f32_16x16x32_bf16 v[100:103], v[146:149], v[216:219], v[100:103]
	v_mfma_f32_16x16x32_bf16 v[92:95], v[160:163], v[216:219], v[92:95]
	v_mfma_f32_16x16x32_bf16 v[84:87], v[146:149], v[224:227], v[84:87]
	v_mfma_f32_16x16x32_bf16 v[76:79], v[160:163], v[224:227], v[76:79]
	s_setprio 0
	s_setprio 1
	v_mfma_f32_16x16x32_bf16 v[112:115], v[164:167], v[196:199], v[112:115]
	v_mfma_f32_16x16x32_bf16 v[104:107], v[172:175], v[196:199], v[104:107]
	v_mfma_f32_16x16x32_bf16 v[96:99], v[164:167], v[204:207], v[96:99]
	v_mfma_f32_16x16x32_bf16 v[88:91], v[172:175], v[204:207], v[88:91]
	v_mfma_f32_16x16x32_bf16 v[80:83], v[164:167], v[212:215], v[80:83]
	v_mfma_f32_16x16x32_bf16 v[72:75], v[172:175], v[212:215], v[72:75]
	v_mfma_f32_16x16x32_bf16 v[68:71], v[164:167], v[220:223], v[68:71]
	v_mfma_f32_16x16x32_bf16 v[64:67], v[172:175], v[220:223], v[64:67]
	v_mfma_f32_16x16x32_bf16 v[112:115], v[168:171], v[200:203], v[112:115]
	v_mfma_f32_16x16x32_bf16 v[104:107], v[192:195], v[200:203], v[104:107]
	v_mfma_f32_16x16x32_bf16 v[96:99], v[168:171], v[208:211], v[96:99]
	v_mfma_f32_16x16x32_bf16 v[88:91], v[192:195], v[208:211], v[88:91]
	v_mfma_f32_16x16x32_bf16 v[80:83], v[168:171], v[216:219], v[80:83]
	v_mfma_f32_16x16x32_bf16 v[72:75], v[192:195], v[216:219], v[72:75]
	v_mfma_f32_16x16x32_bf16 v[68:71], v[168:171], v[224:227], v[68:71]
	v_mfma_f32_16x16x32_bf16 v[64:67], v[192:195], v[224:227], v[64:67]
	s_setprio 0
	s_barrier
; #define PG8_STAGE(bufoff, gbase, voff) do { _Pragma("unroll") for (int _i = 0; _i < 2; ++_i) \
;         __builtin_amdgcn_global_load_lds((const unsigned*)((const char*)(gbase) + (voff)[_i]), (PG8_LAS unsigned*)(lds + (bufoff) + ldsw + _i * 8192), 16, 0, 0); } while (0)
; #define PG8_LDA(dst, b, h) do { _Pragma("unroll") for (int m = 0; m < 4; ++m) _Pragma("unroll") for (int k = 0; k < 2; ++k) dst[m][k] = *(const PG8_LAS bf16x8*)(lds + PG8_SA(b, h) + aoff + m * 2048 + k * 1024); } while (0)
; #define PG8_MMA(ai, bj, At, Bt) do { __builtin_amdgcn_s_setprio(1); _Pragma("unroll") for (int m = 0; m < 4; ++m) _Pragma("unroll") for (int n = 0; n < 2; ++n) _Pragma("unroll") for (int k = 0; k < 2; ++k) \
;         acc[ai][bj][m][n] = __builtin_amdgcn_mfma_f32_16x16x32_bf16(Bt[n][k], At[m][k], acc[ai][bj][m][n], 0, 0, 0); __builtin_amdgcn_s_setprio(0); } while (0)
; #define PG8_WAIT_V(n) asm volatile("s_waitcnt vmcnt(" #n ")" ::: "memory")
; #define PG8_WAIT_L(n) asm volatile("s_waitcnt lgkmcnt(" #n ")" ::: "memory")
; #define PG8_BAR __builtin_amdgcn_s_barrier()
; #define PG8_SCHED __builtin_amdgcn_sched_barrier(0)
; template <class Epi, class Sched, bool ALIGN_EPI = false, bool SP2 = false>
; __device__ __forceinline__ void gemm_phase(PG8_LAS unsigned char* lds, const Gemm g, const Sched& S, const Epi& E) {
;     ...
;         for (int t = 0; t < nt; t += 2) {
;             const bool last = (t == nt - 2);
;             const char* a1 = cA + (size_t)(t + 1) * kstep;
;             const char* a2 = last ? nA : cA + (size_t)(t + 2) * kstep; const char* b2 = last ? nB : cB + (size_t)(t + 2) * kstep;
;             const char* a3 = a2 + kstep; const char* b3 = b2 + kstep;
;     ...
;             PG8_LDA(At, 1, 1); PG8_STAGE(PG8_SB(1, 0), b3, voffB); PG8_STAGE(PG8_SB(1, 1), b3 + hstep, voffB); PG8_STAGE(PG8_SA(1, 0), a3, voffA);
;             PG8_WAIT_V(8); PG8_WAIT_L(0); PG8_BAR; PG8_MMA(1, 0, At, B0); PG8_MMA(1, 1, At, B1); PG8_BAR; PG8_SCHED;
	s_add_i32 s69, s93, s0
	v_lshl_add_u64 v[150:151], v[150:151], 0, s[18:19]
	s_mov_b32 m0, s69
	ds_read_b128 v[196:199], v141 offset:49152
	ds_read_b128 v[200:203], v141 offset:50176
	ds_read_b128 v[204:207], v141 offset:51200
	ds_read_b128 v[208:211], v141 offset:52224
	ds_read_b128 v[212:215], v141 offset:53248
	ds_read_b128 v[216:219], v141 offset:54272
	ds_read_b128 v[220:223], v141 offset:55296
	ds_read_b128 v[224:227], v141 offset:56320
	global_load_lds_dwordx4 v[150:151], off
	s_add_i32 m0, s69, 0x2000
	s_add_u32 s74, s74, 0x80080
	v_lshl_add_u64 v[150:151], v[182:183], 0, s[18:19]
	s_addc_u32 s75, s75, 0
	s_add_i32 s68, s68, s0
	global_load_lds_dwordx4 v[150:151], off
	v_lshl_add_u64 v[150:151], s[74:75], 0, v[152:153]
	v_lshl_add_u64 v[232:233], s[74:75], 0, v[152:153]
	v_lshl_add_u64 v[150:151], s[74:75], 0, v[132:133]
	v_lshl_add_u64 v[234:235], s[74:75], 0, v[132:133]
	v_lshl_add_u64 v[150:151], v[184:185], 0, s[18:19]
	v_lshl_add_u64 v[240:241], v[184:185], 0, s[18:19]
	v_lshl_add_u64 v[150:151], v[188:189], 0, s[18:19]
	v_lshl_add_u64 v[242:243], v[188:189], 0, s[18:19]
	s_waitcnt vmcnt(4)
	s_waitcnt lgkmcnt(0)
	s_barrier
	s_setprio 1
	s_waitcnt lgkmcnt(0)
	v_mfma_f32_16x16x32_bf16 v[60:63], v[142:145], v[196:199], v[60:63]
	s_mov_b32 m0, s68
	v_mfma_f32_16x16x32_bf16 v[56:59], v[156:159], v[196:199], v[56:59]
	global_load_lds_dwordx4 v[232:233], off
	v_mfma_f32_16x16x32_bf16 v[52:55], v[142:145], v[204:207], v[52:55]
	v_mfma_f32_16x16x32_bf16 v[44:47], v[156:159], v[204:207], v[44:47]
	v_mfma_f32_16x16x32_bf16 v[36:39], v[142:145], v[212:215], v[36:39]
	v_mfma_f32_16x16x32_bf16 v[28:31], v[156:159], v[212:215], v[28:31]
	v_mfma_f32_16x16x32_bf16 v[20:23], v[142:145], v[220:223], v[20:23]
	v_mfma_f32_16x16x32_bf16 v[12:15], v[156:159], v[220:223], v[12:15]
	v_mfma_f32_16x16x32_bf16 v[60:63], v[146:149], v[200:203], v[60:63]
	s_add_i32 m0, s68, 0x2000
	v_mfma_f32_16x16x32_bf16 v[56:59], v[160:163], v[200:203], v[56:59]
	global_load_lds_dwordx4 v[234:235], off
	v_mfma_f32_16x16x32_bf16 v[52:55], v[146:149], v[208:211], v[52:55]
	v_mfma_f32_16x16x32_bf16 v[44:47], v[160:163], v[208:211], v[44:47]
	v_mfma_f32_16x16x32_bf16 v[36:39], v[146:149], v[216:219], v[36:39]
	v_mfma_f32_16x16x32_bf16 v[28:31], v[160:163], v[216:219], v[28:31]
	v_mfma_f32_16x16x32_bf16 v[20:23], v[146:149], v[224:227], v[20:23]
	v_mfma_f32_16x16x32_bf16 v[12:15], v[160:163], v[224:227], v[12:15]
	s_setprio 0
	s_setprio 1
	v_mfma_f32_16x16x32_bf16 v[48:51], v[164:167], v[196:199], v[48:51]
	s_mov_b32 m0, s26
	v_mfma_f32_16x16x32_bf16 v[40:43], v[172:175], v[196:199], v[40:43]
	global_load_lds_dwordx4 v[240:241], off
	v_mfma_f32_16x16x32_bf16 v[32:35], v[164:167], v[204:207], v[32:35]
	v_mfma_f32_16x16x32_bf16 v[24:27], v[172:175], v[204:207], v[24:27]
	v_mfma_f32_16x16x32_bf16 v[16:19], v[164:167], v[212:215], v[16:19]
	v_mfma_f32_16x16x32_bf16 v[8:11], v[172:175], v[212:215], v[8:11]
	v_mfma_f32_16x16x32_bf16 v[4:7], v[164:167], v[220:223], v[4:7]
	v_mfma_f32_16x16x32_bf16 v[0:3], v[172:175], v[220:223], v[0:3]
	v_mfma_f32_16x16x32_bf16 v[48:51], v[168:171], v[200:203], v[48:51]
	s_mov_b32 m0, s34
	v_mfma_f32_16x16x32_bf16 v[40:43], v[192:195], v[200:203], v[40:43]
	global_load_lds_dwordx4 v[242:243], off
	v_mfma_f32_16x16x32_bf16 v[32:35], v[168:171], v[208:211], v[32:35]
	v_mfma_f32_16x16x32_bf16 v[24:27], v[192:195], v[208:211], v[24:27]
	v_mfma_f32_16x16x32_bf16 v[16:19], v[168:171], v[216:219], v[16:19]
	v_mfma_f32_16x16x32_bf16 v[8:11], v[192:195], v[216:219], v[8:11]
	v_mfma_f32_16x16x32_bf16 v[4:7], v[168:171], v[224:227], v[4:7]
	v_mfma_f32_16x16x32_bf16 v[0:3], v[192:195], v[224:227], v[0:3]
	s_setprio 0
	s_barrier
	s_add_i32 s71, s71, 2
	s_add_u32 s48, s48, 0x100
	s_addc_u32 s49, s49, 0
	s_add_u32 s59, s59, 0x100
	s_addc_u32 s63, s63, 0
	s_cmp_gt_u32 s71, 29
	s_cbranch_scc0 .LBB0_354
	s_and_b64 vcc, exec, s[28:29]
	s_movk_i32 s58, 0x5fe
	s_movk_i32 s59, 0x1810
	s_cbranch_vccz .LBB0_357
	s_barrier
